# removed the back-to-back s_setprio 0/1 pairs between the two MFMA blocks of each GEMM super-phase (on top of v5)
# speedup vs baseline: 1.0163x; 1.0163x over previous
.LBB0_259:
	s_add_u32 s24, s22, 0xfffc0080
	s_addc_u32 s25, s23, -1
	s_add_i32 s42, 0, 0x10000
	s_cmp_eq_u32 s41, 12
	s_cselect_b32 s27, s0, s25
	s_cselect_b32 s26, s1, s24
	s_cselect_b32 s25, s7, s40
	s_cselect_b32 s24, s9, s37
	s_add_i32 s44, 0, 0x14000
	v_add_u32_e32 v156, s42, v145
	v_add_u32_e32 v172, s44, v145
	ds_read_b128 v[140:143], v156
	ds_read_b128 v[148:151], v156 offset:1024
	ds_read_b128 v[152:155], v156 offset:2048
	ds_read_b128 v[156:159], v156 offset:3072
	ds_read_b128 v[160:163], v172
	ds_read_b128 v[164:167], v172 offset:1024
	ds_read_b128 v[168:171], v172 offset:2048
	ds_read_b128 v[172:175], v172 offset:3072
	v_lshl_add_u64 v[180:181], s[22:23], 0, v[136:137]
	s_add_i32 m0, s13, 0xc000
	ds_read_b128 v[176:179], v147
	ds_read_b128 v[186:189], v147 offset:1024
	ds_read_b128 v[190:193], v147 offset:2048
	ds_read_b128 v[194:197], v147 offset:3072
	ds_read_b128 v[214:217], v147 offset:4096
	ds_read_b128 v[218:221], v147 offset:5120
	ds_read_b128 v[222:225], v147 offset:6144
	ds_read_b128 v[226:229], v147 offset:7168
	global_load_lds_dwordx4 v[180:181], off
	v_lshl_add_u64 v[180:181], s[22:23], 0, v[138:139]
	s_add_i32 m0, s13, 0xe000
	s_nop 0
	global_load_lds_dwordx4 v[180:181], off
	s_waitcnt vmcnt(8)
	s_waitcnt lgkmcnt(0)
	s_barrier
	s_setprio 1
	s_waitcnt lgkmcnt(0)
	v_mfma_f32_16x16x32_bf16 v[126:129], v[140:143], v[176:179], v[126:129]
	v_mfma_f32_16x16x32_bf16 v[122:125], v[152:155], v[176:179], v[122:125]
	v_mfma_f32_16x16x32_bf16 v[118:121], v[140:143], v[190:193], v[118:121]
	v_mfma_f32_16x16x32_bf16 v[110:113], v[152:155], v[190:193], v[110:113]
	v_mfma_f32_16x16x32_bf16 v[102:105], v[140:143], v[214:217], v[102:105]
	v_mfma_f32_16x16x32_bf16 v[94:97], v[152:155], v[214:217], v[94:97]
	v_mfma_f32_16x16x32_bf16 v[86:89], v[140:143], v[222:225], v[86:89]
	v_mfma_f32_16x16x32_bf16 v[78:81], v[152:155], v[222:225], v[78:81]
	v_mfma_f32_16x16x32_bf16 v[126:129], v[148:151], v[186:189], v[126:129]
	v_mfma_f32_16x16x32_bf16 v[122:125], v[156:159], v[186:189], v[122:125]
	v_mfma_f32_16x16x32_bf16 v[118:121], v[148:151], v[194:197], v[118:121]
	v_mfma_f32_16x16x32_bf16 v[110:113], v[156:159], v[194:197], v[110:113]
	v_mfma_f32_16x16x32_bf16 v[102:105], v[148:151], v[218:221], v[102:105]
	v_mfma_f32_16x16x32_bf16 v[94:97], v[156:159], v[218:221], v[94:97]
	v_mfma_f32_16x16x32_bf16 v[86:89], v[148:151], v[226:229], v[86:89]
	v_mfma_f32_16x16x32_bf16 v[78:81], v[156:159], v[226:229], v[78:81]
	v_mfma_f32_16x16x32_bf16 v[114:117], v[160:163], v[176:179], v[114:117]
	v_mfma_f32_16x16x32_bf16 v[106:109], v[168:171], v[176:179], v[106:109]
	v_mfma_f32_16x16x32_bf16 v[98:101], v[160:163], v[190:193], v[98:101]
	v_mfma_f32_16x16x32_bf16 v[90:93], v[168:171], v[190:193], v[90:93]
	v_mfma_f32_16x16x32_bf16 v[82:85], v[160:163], v[214:217], v[82:85]
	v_mfma_f32_16x16x32_bf16 v[74:77], v[168:171], v[214:217], v[74:77]
	v_mfma_f32_16x16x32_bf16 v[70:73], v[160:163], v[222:225], v[70:73]
	v_mfma_f32_16x16x32_bf16 v[66:69], v[168:171], v[222:225], v[66:69]
	v_mfma_f32_16x16x32_bf16 v[114:117], v[164:167], v[186:189], v[114:117]
	v_mfma_f32_16x16x32_bf16 v[106:109], v[172:175], v[186:189], v[106:109]
	v_mfma_f32_16x16x32_bf16 v[98:101], v[164:167], v[194:197], v[98:101]
	v_mfma_f32_16x16x32_bf16 v[90:93], v[172:175], v[194:197], v[90:93]
	v_mfma_f32_16x16x32_bf16 v[82:85], v[164:167], v[218:221], v[82:85]
	v_mfma_f32_16x16x32_bf16 v[74:77], v[172:175], v[218:221], v[74:77]
	v_mfma_f32_16x16x32_bf16 v[70:73], v[164:167], v[226:229], v[70:73]
	v_mfma_f32_16x16x32_bf16 v[66:69], v[172:175], v[226:229], v[66:69]
	s_setprio 0
	s_barrier
	s_add_i32 s42, s42, s12
	v_lshl_add_u64 v[180:181], s[24:25], 0, v[0:1]
	s_mov_b32 m0, s42
	ds_read_b128 v[176:179], v147 offset:16384
	ds_read_b128 v[186:189], v147 offset:17408
	ds_read_b128 v[190:193], v147 offset:18432
	ds_read_b128 v[194:197], v147 offset:19456
	ds_read_b128 v[214:217], v147 offset:20480
	ds_read_b128 v[218:221], v147 offset:21504
	ds_read_b128 v[222:225], v147 offset:22528
	ds_read_b128 v[226:229], v147 offset:23552
	global_load_lds_dwordx4 v[180:181], off
	s_add_i32 m0, s42, 0x2000
	s_add_u32 s42, s24, 0x40000
	v_lshl_add_u64 v[230:231], s[24:25], 0, v[130:131]
	s_addc_u32 s43, s25, 0
	s_add_i32 s44, s44, s12
	global_load_lds_dwordx4 v[230:231], off
	v_lshl_add_u64 v[232:233], s[42:43], 0, v[0:1]
	s_mov_b32 m0, s44
	v_lshl_add_u64 v[234:235], s[26:27], 0, v[132:133]
	global_load_lds_dwordx4 v[232:233], off
	v_lshl_add_u64 v[232:233], s[42:43], 0, v[130:131]
	s_add_i32 m0, s44, 0x2000
	s_nop 0
	global_load_lds_dwordx4 v[232:233], off
	v_lshl_add_u64 v[232:233], s[26:27], 0, v[134:135]
	s_mov_b32 m0, s13
	s_nop 0
	global_load_lds_dwordx4 v[232:233], off
	s_mov_b32 m0, s14
	s_nop 0
	global_load_lds_dwordx4 v[234:235], off
	s_waitcnt vmcnt(8)
	s_waitcnt lgkmcnt(0)
	s_barrier
	s_setprio 1
	s_waitcnt lgkmcnt(0)
	v_mfma_f32_16x16x32_bf16 v[62:65], v[140:143], v[176:179], v[62:65]
	v_mfma_f32_16x16x32_bf16 v[58:61], v[152:155], v[176:179], v[58:61]
	v_mfma_f32_16x16x32_bf16 v[54:57], v[140:143], v[190:193], v[54:57]
	v_mfma_f32_16x16x32_bf16 v[46:49], v[152:155], v[190:193], v[46:49]
	v_mfma_f32_16x16x32_bf16 v[38:41], v[140:143], v[214:217], v[38:41]
	v_mfma_f32_16x16x32_bf16 v[30:33], v[152:155], v[214:217], v[30:33]
	v_mfma_f32_16x16x32_bf16 v[22:25], v[140:143], v[222:225], v[22:25]
	v_mfma_f32_16x16x32_bf16 v[14:17], v[152:155], v[222:225], v[14:17]
	v_mfma_f32_16x16x32_bf16 v[62:65], v[148:151], v[186:189], v[62:65]
	v_mfma_f32_16x16x32_bf16 v[58:61], v[156:159], v[186:189], v[58:61]
	v_mfma_f32_16x16x32_bf16 v[54:57], v[148:151], v[194:197], v[54:57]
	v_mfma_f32_16x16x32_bf16 v[46:49], v[156:159], v[194:197], v[46:49]
	v_mfma_f32_16x16x32_bf16 v[38:41], v[148:151], v[218:221], v[38:41]
	v_mfma_f32_16x16x32_bf16 v[30:33], v[156:159], v[218:221], v[30:33]
	v_mfma_f32_16x16x32_bf16 v[22:25], v[148:151], v[226:229], v[22:25]
	v_mfma_f32_16x16x32_bf16 v[14:17], v[156:159], v[226:229], v[14:17]
	v_mfma_f32_16x16x32_bf16 v[50:53], v[160:163], v[176:179], v[50:53]
	v_mfma_f32_16x16x32_bf16 v[42:45], v[168:171], v[176:179], v[42:45]
	v_mfma_f32_16x16x32_bf16 v[34:37], v[160:163], v[190:193], v[34:37]
	v_mfma_f32_16x16x32_bf16 v[26:29], v[168:171], v[190:193], v[26:29]
	v_mfma_f32_16x16x32_bf16 v[18:21], v[160:163], v[214:217], v[18:21]
	v_mfma_f32_16x16x32_bf16 v[10:13], v[168:171], v[214:217], v[10:13]
	v_mfma_f32_16x16x32_bf16 v[6:9], v[160:163], v[222:225], v[6:9]
	v_mfma_f32_16x16x32_bf16 v[2:5], v[168:171], v[222:225], v[2:5]
	v_mfma_f32_16x16x32_bf16 v[50:53], v[164:167], v[186:189], v[50:53]
	v_mfma_f32_16x16x32_bf16 v[42:45], v[172:175], v[186:189], v[42:45]
	v_mfma_f32_16x16x32_bf16 v[34:37], v[164:167], v[194:197], v[34:37]
	v_mfma_f32_16x16x32_bf16 v[26:29], v[172:175], v[194:197], v[26:29]
	v_mfma_f32_16x16x32_bf16 v[18:21], v[164:167], v[218:221], v[18:21]
	v_mfma_f32_16x16x32_bf16 v[10:13], v[172:175], v[218:221], v[10:13]
	v_mfma_f32_16x16x32_bf16 v[6:9], v[164:167], v[226:229], v[6:9]
	v_mfma_f32_16x16x32_bf16 v[2:5], v[172:175], v[226:229], v[2:5]
	s_setprio 0
	s_barrier
	s_add_i32 s42, 0, 0x18000
	s_add_i32 s43, 0, 0x1c000
	v_add_u32_e32 v156, s42, v145
	v_add_u32_e32 v172, s43, v145
	ds_read_b128 v[140:143], v156
	ds_read_b128 v[148:151], v156 offset:1024
	ds_read_b128 v[152:155], v156 offset:2048
	ds_read_b128 v[156:159], v156 offset:3072
	ds_read_b128 v[160:163], v172
	ds_read_b128 v[164:167], v172 offset:1024
	ds_read_b128 v[168:171], v172 offset:2048
	ds_read_b128 v[172:175], v172 offset:3072
	s_add_u32 s26, s26, 0x40000
	s_addc_u32 s27, s27, 0
	s_mov_b32 m0, s28
	v_lshl_add_u64 v[240:241], s[26:27], 0, v[134:135]
	ds_read_b128 v[176:179], v147 offset:32768
	ds_read_b128 v[186:189], v147 offset:33792
	ds_read_b128 v[190:193], v147 offset:34816
	ds_read_b128 v[194:197], v147 offset:35840
	ds_read_b128 v[214:217], v147 offset:36864
	ds_read_b128 v[218:221], v147 offset:37888
	ds_read_b128 v[222:225], v147 offset:38912
	ds_read_b128 v[226:229], v147 offset:39936
	global_load_lds_dwordx4 v[240:241], off
	v_lshl_add_u64 v[240:241], s[26:27], 0, v[132:133]
	s_mov_b32 m0, s29
	s_nop 0
	global_load_lds_dwordx4 v[240:241], off
	s_waitcnt vmcnt(8)
	s_waitcnt lgkmcnt(0)
	s_barrier
	s_setprio 1
	s_waitcnt lgkmcnt(0)
	v_mfma_f32_16x16x32_bf16 v[126:129], v[140:143], v[176:179], v[126:129]
	v_mfma_f32_16x16x32_bf16 v[122:125], v[152:155], v[176:179], v[122:125]
	v_mfma_f32_16x16x32_bf16 v[118:121], v[140:143], v[190:193], v[118:121]
	v_mfma_f32_16x16x32_bf16 v[110:113], v[152:155], v[190:193], v[110:113]
	v_mfma_f32_16x16x32_bf16 v[102:105], v[140:143], v[214:217], v[102:105]
	v_mfma_f32_16x16x32_bf16 v[94:97], v[152:155], v[214:217], v[94:97]
	v_mfma_f32_16x16x32_bf16 v[86:89], v[140:143], v[222:225], v[86:89]
	v_mfma_f32_16x16x32_bf16 v[78:81], v[152:155], v[222:225], v[78:81]
	v_mfma_f32_16x16x32_bf16 v[126:129], v[148:151], v[186:189], v[126:129]
	v_mfma_f32_16x16x32_bf16 v[122:125], v[156:159], v[186:189], v[122:125]
	v_mfma_f32_16x16x32_bf16 v[118:121], v[148:151], v[194:197], v[118:121]
	v_mfma_f32_16x16x32_bf16 v[110:113], v[156:159], v[194:197], v[110:113]
	v_mfma_f32_16x16x32_bf16 v[102:105], v[148:151], v[218:221], v[102:105]
	v_mfma_f32_16x16x32_bf16 v[94:97], v[156:159], v[218:221], v[94:97]
	v_mfma_f32_16x16x32_bf16 v[86:89], v[148:151], v[226:229], v[86:89]
	v_mfma_f32_16x16x32_bf16 v[78:81], v[156:159], v[226:229], v[78:81]
	v_mfma_f32_16x16x32_bf16 v[114:117], v[160:163], v[176:179], v[114:117]
	v_mfma_f32_16x16x32_bf16 v[106:109], v[168:171], v[176:179], v[106:109]
	v_mfma_f32_16x16x32_bf16 v[98:101], v[160:163], v[190:193], v[98:101]
	v_mfma_f32_16x16x32_bf16 v[90:93], v[168:171], v[190:193], v[90:93]
	v_mfma_f32_16x16x32_bf16 v[82:85], v[160:163], v[214:217], v[82:85]
	v_mfma_f32_16x16x32_bf16 v[74:77], v[168:171], v[214:217], v[74:77]
	v_mfma_f32_16x16x32_bf16 v[70:73], v[160:163], v[222:225], v[70:73]
	v_mfma_f32_16x16x32_bf16 v[66:69], v[168:171], v[222:225], v[66:69]
	v_mfma_f32_16x16x32_bf16 v[114:117], v[164:167], v[186:189], v[114:117]
	v_mfma_f32_16x16x32_bf16 v[106:109], v[172:175], v[186:189], v[106:109]
	v_mfma_f32_16x16x32_bf16 v[98:101], v[164:167], v[194:197], v[98:101]
	v_mfma_f32_16x16x32_bf16 v[90:93], v[172:175], v[194:197], v[90:93]
	v_mfma_f32_16x16x32_bf16 v[82:85], v[164:167], v[218:221], v[82:85]
	v_mfma_f32_16x16x32_bf16 v[74:77], v[172:175], v[218:221], v[74:77]
	v_mfma_f32_16x16x32_bf16 v[70:73], v[164:167], v[226:229], v[70:73]
	v_mfma_f32_16x16x32_bf16 v[66:69], v[172:175], v[226:229], v[66:69]
	s_setprio 0
	s_barrier
	s_add_i32 s26, s42, s12
	v_lshl_add_u64 v[180:181], v[180:181], 0, s[54:55]
	s_mov_b32 m0, s26
	ds_read_b128 v[176:179], v147 offset:49152
	ds_read_b128 v[186:189], v147 offset:50176
	ds_read_b128 v[190:193], v147 offset:51200
	ds_read_b128 v[194:197], v147 offset:52224
	ds_read_b128 v[214:217], v147 offset:53248
	ds_read_b128 v[218:221], v147 offset:54272
	ds_read_b128 v[222:225], v147 offset:55296
	ds_read_b128 v[226:229], v147 offset:56320
	global_load_lds_dwordx4 v[180:181], off
	s_add_i32 m0, s26, 0x2000
	s_add_u32 s24, s24, 0x40080
	v_lshl_add_u64 v[180:181], v[230:231], 0, s[54:55]
	s_addc_u32 s25, s25, 0
	s_add_i32 s26, s43, s12
	global_load_lds_dwordx4 v[180:181], off
	v_lshl_add_u64 v[180:181], s[24:25], 0, v[0:1]
	s_mov_b32 m0, s26
	s_nop 0
	global_load_lds_dwordx4 v[180:181], off
	v_lshl_add_u64 v[180:181], s[24:25], 0, v[130:131]
	s_add_i32 m0, s26, 0x2000
	s_nop 0
	global_load_lds_dwordx4 v[180:181], off
	v_lshl_add_u64 v[180:181], v[232:233], 0, s[54:55]
	s_mov_b32 m0, s30
	s_nop 0
	global_load_lds_dwordx4 v[180:181], off
	v_lshl_add_u64 v[180:181], v[234:235], 0, s[54:55]
	s_mov_b32 m0, s31
	s_nop 0
	global_load_lds_dwordx4 v[180:181], off
	s_waitcnt vmcnt(8)
	s_waitcnt lgkmcnt(0)
	s_barrier
	s_setprio 1
	s_waitcnt lgkmcnt(0)
	v_mfma_f32_16x16x32_bf16 v[62:65], v[140:143], v[176:179], v[62:65]
	v_mfma_f32_16x16x32_bf16 v[58:61], v[152:155], v[176:179], v[58:61]
	v_mfma_f32_16x16x32_bf16 v[54:57], v[140:143], v[190:193], v[54:57]
	v_mfma_f32_16x16x32_bf16 v[46:49], v[152:155], v[190:193], v[46:49]
	v_mfma_f32_16x16x32_bf16 v[38:41], v[140:143], v[214:217], v[38:41]
	v_mfma_f32_16x16x32_bf16 v[30:33], v[152:155], v[214:217], v[30:33]
	v_mfma_f32_16x16x32_bf16 v[22:25], v[140:143], v[222:225], v[22:25]
	v_mfma_f32_16x16x32_bf16 v[14:17], v[152:155], v[222:225], v[14:17]
	v_mfma_f32_16x16x32_bf16 v[62:65], v[148:151], v[186:189], v[62:65]
	v_mfma_f32_16x16x32_bf16 v[58:61], v[156:159], v[186:189], v[58:61]
	v_mfma_f32_16x16x32_bf16 v[54:57], v[148:151], v[194:197], v[54:57]
	v_mfma_f32_16x16x32_bf16 v[46:49], v[156:159], v[194:197], v[46:49]
	v_mfma_f32_16x16x32_bf16 v[38:41], v[148:151], v[218:221], v[38:41]
	v_mfma_f32_16x16x32_bf16 v[30:33], v[156:159], v[218:221], v[30:33]
	v_mfma_f32_16x16x32_bf16 v[22:25], v[148:151], v[226:229], v[22:25]
	v_mfma_f32_16x16x32_bf16 v[14:17], v[156:159], v[226:229], v[14:17]
	v_mfma_f32_16x16x32_bf16 v[50:53], v[160:163], v[176:179], v[50:53]
	v_mfma_f32_16x16x32_bf16 v[42:45], v[168:171], v[176:179], v[42:45]
	v_mfma_f32_16x16x32_bf16 v[34:37], v[160:163], v[190:193], v[34:37]
	v_mfma_f32_16x16x32_bf16 v[26:29], v[168:171], v[190:193], v[26:29]
	v_mfma_f32_16x16x32_bf16 v[18:21], v[160:163], v[214:217], v[18:21]
	v_mfma_f32_16x16x32_bf16 v[10:13], v[168:171], v[214:217], v[10:13]
	v_mfma_f32_16x16x32_bf16 v[6:9], v[160:163], v[222:225], v[6:9]
	v_mfma_f32_16x16x32_bf16 v[2:5], v[168:171], v[222:225], v[2:5]
	v_mfma_f32_16x16x32_bf16 v[50:53], v[164:167], v[186:189], v[50:53]
	v_mfma_f32_16x16x32_bf16 v[42:45], v[172:175], v[186:189], v[42:45]
	v_mfma_f32_16x16x32_bf16 v[34:37], v[164:167], v[194:197], v[34:37]
	v_mfma_f32_16x16x32_bf16 v[26:29], v[172:175], v[194:197], v[26:29]
	v_mfma_f32_16x16x32_bf16 v[18:21], v[164:167], v[218:221], v[18:21]
	v_mfma_f32_16x16x32_bf16 v[10:13], v[172:175], v[218:221], v[10:13]
	v_mfma_f32_16x16x32_bf16 v[6:9], v[164:167], v[226:229], v[6:9]
	v_mfma_f32_16x16x32_bf16 v[2:5], v[172:175], v[226:229], v[2:5]
	s_setprio 0
	s_barrier
	s_add_i32 s41, s41, 2
	s_add_u32 s22, s22, 0x100
	s_addc_u32 s23, s23, 0
	s_add_u32 s37, s37, 0x100
	s_addc_u32 s40, s40, 0
	s_cmp_gt_u32 s41, 13
	s_cbranch_scc0 .LBB0_259
	s_and_b64 vcc, exec, s[4:5]
	s_cbranch_vccz .LBB0_262
	s_barrier

.LBB0_1022:
	s_add_u32 s16, s2, 0x100
	s_addc_u32 s17, s3, 0
	s_add_i32 s18, 0, 0x10000
	s_cmp_eq_u32 s37, 12
	s_cselect_b32 s25, s0, s17
	s_cselect_b32 s24, s1, s16
	v_add_u32_e32 v159, s18, v156
	s_cselect_b32 s23, s5, s36
	s_cselect_b32 s22, s7, s35
	s_add_i32 s19, 0, 0x14000
	ds_read_b128 v[152:155], v159
	ds_read_b128 v[160:163], v159 offset:1024
	ds_read_b128 v[164:167], v159 offset:2048
	ds_read_b128 v[168:171], v159 offset:3072
	v_add_u32_e32 v159, s19, v156
	ds_read_b128 v[172:175], v159
	ds_read_b128 v[176:179], v159 offset:1024
	ds_read_b128 v[186:189], v159 offset:2048
	ds_read_b128 v[190:193], v159 offset:3072
	v_lshl_add_u64 v[180:181], s[2:3], 0, v[148:149]
	s_add_i32 m0, s26, 0xc000
	ds_read_b128 v[194:197], v158
	ds_read_b128 v[214:217], v158 offset:1024
	ds_read_b128 v[218:221], v158 offset:2048
	ds_read_b128 v[222:225], v158 offset:3072
	ds_read_b128 v[226:229], v158 offset:4096
	ds_read_b128 v[230:233], v158 offset:5120
	ds_read_b128 v[240:243], v158 offset:6144
	ds_read_b128 v[244:247], v158 offset:7168
	global_load_lds_dwordx4 v[180:181], off
	v_lshl_add_u64 v[180:181], s[2:3], 0, v[150:151]
	s_add_i32 m0, s26, 0xe000
	s_nop 0
	global_load_lds_dwordx4 v[180:181], off
	s_waitcnt vmcnt(8)
	s_waitcnt lgkmcnt(0)
	s_barrier
	s_setprio 1
	s_waitcnt lgkmcnt(0)
	v_mfma_f32_16x16x32_bf16 v[126:129], v[152:155], v[194:197], v[126:129]
	v_mfma_f32_16x16x32_bf16 v[102:105], v[164:167], v[194:197], v[102:105]
	v_mfma_f32_16x16x32_bf16 v[122:125], v[152:155], v[218:221], v[122:125]
	v_mfma_f32_16x16x32_bf16 v[90:93], v[164:167], v[218:221], v[90:93]
	v_mfma_f32_16x16x32_bf16 v[118:121], v[152:155], v[226:229], v[118:121]
	v_mfma_f32_16x16x32_bf16 v[86:89], v[164:167], v[226:229], v[86:89]
	v_mfma_f32_16x16x32_bf16 v[114:117], v[152:155], v[240:243], v[114:117]
	v_mfma_f32_16x16x32_bf16 v[82:85], v[164:167], v[240:243], v[82:85]
	v_mfma_f32_16x16x32_bf16 v[126:129], v[160:163], v[214:217], v[126:129]
	v_mfma_f32_16x16x32_bf16 v[102:105], v[168:171], v[214:217], v[102:105]
	v_mfma_f32_16x16x32_bf16 v[122:125], v[160:163], v[222:225], v[122:125]
	v_mfma_f32_16x16x32_bf16 v[90:93], v[168:171], v[222:225], v[90:93]
	v_mfma_f32_16x16x32_bf16 v[118:121], v[160:163], v[230:233], v[118:121]
	v_mfma_f32_16x16x32_bf16 v[86:89], v[168:171], v[230:233], v[86:89]
	v_mfma_f32_16x16x32_bf16 v[114:117], v[160:163], v[244:247], v[114:117]
	v_mfma_f32_16x16x32_bf16 v[82:85], v[168:171], v[244:247], v[82:85]
	v_mfma_f32_16x16x32_bf16 v[62:65], v[172:175], v[194:197], v[62:65]
	v_mfma_f32_16x16x32_bf16 v[38:41], v[186:189], v[194:197], v[38:41]
	v_mfma_f32_16x16x32_bf16 v[58:61], v[172:175], v[218:221], v[58:61]
	v_mfma_f32_16x16x32_bf16 v[26:29], v[186:189], v[218:221], v[26:29]
	v_mfma_f32_16x16x32_bf16 v[54:57], v[172:175], v[226:229], v[54:57]
	v_mfma_f32_16x16x32_bf16 v[22:25], v[186:189], v[226:229], v[22:25]
	v_mfma_f32_16x16x32_bf16 v[50:53], v[172:175], v[240:243], v[50:53]
	v_mfma_f32_16x16x32_bf16 v[18:21], v[186:189], v[240:243], v[18:21]
	v_mfma_f32_16x16x32_bf16 v[62:65], v[176:179], v[214:217], v[62:65]
	v_mfma_f32_16x16x32_bf16 v[38:41], v[190:193], v[214:217], v[38:41]
	v_mfma_f32_16x16x32_bf16 v[58:61], v[176:179], v[222:225], v[58:61]
	v_mfma_f32_16x16x32_bf16 v[26:29], v[190:193], v[222:225], v[26:29]
	v_mfma_f32_16x16x32_bf16 v[54:57], v[176:179], v[230:233], v[54:57]
	v_mfma_f32_16x16x32_bf16 v[22:25], v[190:193], v[230:233], v[22:25]
	v_mfma_f32_16x16x32_bf16 v[50:53], v[176:179], v[244:247], v[50:53]
	v_mfma_f32_16x16x32_bf16 v[18:21], v[190:193], v[244:247], v[18:21]
	s_setprio 0
	s_barrier
	s_add_i32 s2, s18, s14
	v_lshl_add_u64 v[180:181], s[22:23], 0, v[0:1]
	s_mov_b32 m0, s2
	ds_read_b128 v[194:197], v158 offset:16384
	ds_read_b128 v[214:217], v158 offset:17408
	ds_read_b128 v[218:221], v158 offset:18432
	ds_read_b128 v[222:225], v158 offset:19456
	ds_read_b128 v[226:229], v158 offset:20480
	ds_read_b128 v[230:233], v158 offset:21504
	ds_read_b128 v[240:243], v158 offset:22528
	ds_read_b128 v[244:247], v158 offset:23552
	global_load_lds_dwordx4 v[180:181], off
	s_add_i32 m0, s2, 0x2000
	s_add_u32 s2, s22, 0x40000
	v_lshl_add_u64 v[234:235], s[22:23], 0, v[130:131]
	s_addc_u32 s3, s23, 0
	s_add_i32 s18, s19, s14
	global_load_lds_dwordx4 v[234:235], off
	v_lshl_add_u64 v[210:211], s[2:3], 0, v[0:1]
	s_mov_b32 m0, s18
	v_lshl_add_u64 v[182:183], s[24:25], 0, v[130:131]
	global_load_lds_dwordx4 v[210:211], off
	v_lshl_add_u64 v[210:211], s[2:3], 0, v[130:131]
	s_add_i32 m0, s18, 0x2000
	s_nop 0
	global_load_lds_dwordx4 v[210:211], off
	v_lshl_add_u64 v[210:211], s[24:25], 0, v[0:1]
	s_mov_b32 m0, s26
	s_nop 0
	global_load_lds_dwordx4 v[210:211], off
	s_mov_b32 m0, s27
	s_nop 0
	global_load_lds_dwordx4 v[182:183], off
	s_waitcnt vmcnt(8)
	s_waitcnt lgkmcnt(0)
	s_barrier
	s_setprio 1
	s_waitcnt lgkmcnt(0)
	v_mfma_f32_16x16x32_bf16 v[110:113], v[152:155], v[194:197], v[110:113]
	v_mfma_f32_16x16x32_bf16 v[78:81], v[164:167], v[194:197], v[78:81]
	v_mfma_f32_16x16x32_bf16 v[106:109], v[152:155], v[218:221], v[106:109]
	v_mfma_f32_16x16x32_bf16 v[74:77], v[164:167], v[218:221], v[74:77]
	v_mfma_f32_16x16x32_bf16 v[98:101], v[152:155], v[226:229], v[98:101]
	v_mfma_f32_16x16x32_bf16 v[70:73], v[164:167], v[226:229], v[70:73]
	v_mfma_f32_16x16x32_bf16 v[94:97], v[152:155], v[240:243], v[94:97]
	v_mfma_f32_16x16x32_bf16 v[66:69], v[164:167], v[240:243], v[66:69]
	v_mfma_f32_16x16x32_bf16 v[110:113], v[160:163], v[214:217], v[110:113]
	v_mfma_f32_16x16x32_bf16 v[78:81], v[168:171], v[214:217], v[78:81]
	v_mfma_f32_16x16x32_bf16 v[106:109], v[160:163], v[222:225], v[106:109]
	v_mfma_f32_16x16x32_bf16 v[74:77], v[168:171], v[222:225], v[74:77]
	v_mfma_f32_16x16x32_bf16 v[98:101], v[160:163], v[230:233], v[98:101]
	v_mfma_f32_16x16x32_bf16 v[70:73], v[168:171], v[230:233], v[70:73]
	v_mfma_f32_16x16x32_bf16 v[94:97], v[160:163], v[244:247], v[94:97]
	v_mfma_f32_16x16x32_bf16 v[66:69], v[168:171], v[244:247], v[66:69]
	v_mfma_f32_16x16x32_bf16 v[46:49], v[172:175], v[194:197], v[46:49]
	v_mfma_f32_16x16x32_bf16 v[14:17], v[186:189], v[194:197], v[14:17]
	v_mfma_f32_16x16x32_bf16 v[42:45], v[172:175], v[218:221], v[42:45]
	v_mfma_f32_16x16x32_bf16 v[10:13], v[186:189], v[218:221], v[10:13]
	v_mfma_f32_16x16x32_bf16 v[34:37], v[172:175], v[226:229], v[34:37]
	v_mfma_f32_16x16x32_bf16 v[6:9], v[186:189], v[226:229], v[6:9]
	v_mfma_f32_16x16x32_bf16 v[30:33], v[172:175], v[240:243], v[30:33]
	v_mfma_f32_16x16x32_bf16 v[2:5], v[186:189], v[240:243], v[2:5]
	v_mfma_f32_16x16x32_bf16 v[46:49], v[176:179], v[214:217], v[46:49]
	v_mfma_f32_16x16x32_bf16 v[14:17], v[190:193], v[214:217], v[14:17]
	v_mfma_f32_16x16x32_bf16 v[42:45], v[176:179], v[222:225], v[42:45]
	v_mfma_f32_16x16x32_bf16 v[10:13], v[190:193], v[222:225], v[10:13]
	v_mfma_f32_16x16x32_bf16 v[34:37], v[176:179], v[230:233], v[34:37]
	v_mfma_f32_16x16x32_bf16 v[6:9], v[190:193], v[230:233], v[6:9]
	v_mfma_f32_16x16x32_bf16 v[30:33], v[176:179], v[244:247], v[30:33]
	v_mfma_f32_16x16x32_bf16 v[2:5], v[190:193], v[244:247], v[2:5]
	s_setprio 0
	s_barrier
	s_add_i32 s18, 0, 0x18000
	v_add_u32_e32 v159, s18, v156
	s_add_i32 s19, 0, 0x1c000
	ds_read_b128 v[152:155], v159
	ds_read_b128 v[160:163], v159 offset:1024
	ds_read_b128 v[164:167], v159 offset:2048
	ds_read_b128 v[168:171], v159 offset:3072
	v_add_u32_e32 v159, s19, v156
	ds_read_b128 v[172:175], v159
	ds_read_b128 v[176:179], v159 offset:1024
	ds_read_b128 v[186:189], v159 offset:2048
	ds_read_b128 v[190:193], v159 offset:3072
	s_add_u32 s2, s24, 0x40000
	s_addc_u32 s3, s25, 0
	s_mov_b32 m0, s28
	v_lshl_add_u64 v[184:185], s[2:3], 0, v[0:1]
	ds_read_b128 v[194:197], v158 offset:32768
	ds_read_b128 v[214:217], v158 offset:33792
	ds_read_b128 v[218:221], v158 offset:34816
	ds_read_b128 v[222:225], v158 offset:35840
	ds_read_b128 v[226:229], v158 offset:36864
	ds_read_b128 v[230:233], v158 offset:37888
	ds_read_b128 v[240:243], v158 offset:38912
	ds_read_b128 v[244:247], v158 offset:39936
	global_load_lds_dwordx4 v[184:185], off
	v_lshl_add_u64 v[184:185], s[2:3], 0, v[130:131]
	s_mov_b32 m0, s29
	s_nop 0
	global_load_lds_dwordx4 v[184:185], off
	s_waitcnt vmcnt(8)
	s_waitcnt lgkmcnt(0)
	s_barrier
	s_setprio 1
	s_waitcnt lgkmcnt(0)
	v_mfma_f32_16x16x32_bf16 v[126:129], v[152:155], v[194:197], v[126:129]
	v_mfma_f32_16x16x32_bf16 v[102:105], v[164:167], v[194:197], v[102:105]
	v_mfma_f32_16x16x32_bf16 v[122:125], v[152:155], v[218:221], v[122:125]
	v_mfma_f32_16x16x32_bf16 v[90:93], v[164:167], v[218:221], v[90:93]
	v_mfma_f32_16x16x32_bf16 v[118:121], v[152:155], v[226:229], v[118:121]
	v_mfma_f32_16x16x32_bf16 v[86:89], v[164:167], v[226:229], v[86:89]
	v_mfma_f32_16x16x32_bf16 v[114:117], v[152:155], v[240:243], v[114:117]
	v_mfma_f32_16x16x32_bf16 v[82:85], v[164:167], v[240:243], v[82:85]
	v_mfma_f32_16x16x32_bf16 v[126:129], v[160:163], v[214:217], v[126:129]
	v_mfma_f32_16x16x32_bf16 v[102:105], v[168:171], v[214:217], v[102:105]
	v_mfma_f32_16x16x32_bf16 v[122:125], v[160:163], v[222:225], v[122:125]
	v_mfma_f32_16x16x32_bf16 v[90:93], v[168:171], v[222:225], v[90:93]
	v_mfma_f32_16x16x32_bf16 v[118:121], v[160:163], v[230:233], v[118:121]
	v_mfma_f32_16x16x32_bf16 v[86:89], v[168:171], v[230:233], v[86:89]
	v_mfma_f32_16x16x32_bf16 v[114:117], v[160:163], v[244:247], v[114:117]
	v_mfma_f32_16x16x32_bf16 v[82:85], v[168:171], v[244:247], v[82:85]
	v_mfma_f32_16x16x32_bf16 v[62:65], v[172:175], v[194:197], v[62:65]
	v_mfma_f32_16x16x32_bf16 v[38:41], v[186:189], v[194:197], v[38:41]
	v_mfma_f32_16x16x32_bf16 v[58:61], v[172:175], v[218:221], v[58:61]
	v_mfma_f32_16x16x32_bf16 v[26:29], v[186:189], v[218:221], v[26:29]
	v_mfma_f32_16x16x32_bf16 v[54:57], v[172:175], v[226:229], v[54:57]
	v_mfma_f32_16x16x32_bf16 v[22:25], v[186:189], v[226:229], v[22:25]
	v_mfma_f32_16x16x32_bf16 v[50:53], v[172:175], v[240:243], v[50:53]
	v_mfma_f32_16x16x32_bf16 v[18:21], v[186:189], v[240:243], v[18:21]
	v_mfma_f32_16x16x32_bf16 v[62:65], v[176:179], v[214:217], v[62:65]
	v_mfma_f32_16x16x32_bf16 v[38:41], v[190:193], v[214:217], v[38:41]
	v_mfma_f32_16x16x32_bf16 v[58:61], v[176:179], v[222:225], v[58:61]
	v_mfma_f32_16x16x32_bf16 v[26:29], v[190:193], v[222:225], v[26:29]
	v_mfma_f32_16x16x32_bf16 v[54:57], v[176:179], v[230:233], v[54:57]
	v_mfma_f32_16x16x32_bf16 v[22:25], v[190:193], v[230:233], v[22:25]
	v_mfma_f32_16x16x32_bf16 v[50:53], v[176:179], v[244:247], v[50:53]
	v_mfma_f32_16x16x32_bf16 v[18:21], v[190:193], v[244:247], v[18:21]
	s_setprio 0
	s_barrier
	s_add_i32 s2, s18, s14
	v_lshl_add_u64 v[180:181], v[180:181], 0, s[54:55]
	s_mov_b32 m0, s2
	ds_read_b128 v[194:197], v158 offset:49152
	ds_read_b128 v[214:217], v158 offset:50176
	ds_read_b128 v[218:221], v158 offset:51200
	ds_read_b128 v[222:225], v158 offset:52224
	ds_read_b128 v[226:229], v158 offset:53248
	ds_read_b128 v[230:233], v158 offset:54272
	ds_read_b128 v[240:243], v158 offset:55296
	ds_read_b128 v[244:247], v158 offset:56320
	global_load_lds_dwordx4 v[180:181], off
	s_add_i32 m0, s2, 0x2000
	s_add_u32 s2, s22, 0x40080
	v_lshl_add_u64 v[180:181], v[234:235], 0, s[54:55]
	s_addc_u32 s3, s23, 0
	s_add_i32 s18, s19, s14
	global_load_lds_dwordx4 v[180:181], off
	v_lshl_add_u64 v[180:181], s[2:3], 0, v[0:1]
	s_mov_b32 m0, s18
	s_nop 0
	global_load_lds_dwordx4 v[180:181], off
	v_lshl_add_u64 v[180:181], s[2:3], 0, v[130:131]
	s_add_i32 m0, s18, 0x2000
	s_nop 0
	global_load_lds_dwordx4 v[180:181], off
	v_lshl_add_u64 v[180:181], v[210:211], 0, s[54:55]
	s_mov_b32 m0, s30
	s_nop 0
	global_load_lds_dwordx4 v[180:181], off
	v_lshl_add_u64 v[180:181], v[182:183], 0, s[54:55]
	s_mov_b32 m0, s31
	s_nop 0
	global_load_lds_dwordx4 v[180:181], off
	s_waitcnt vmcnt(8)
	s_waitcnt lgkmcnt(0)
	s_barrier
	s_setprio 1
	s_waitcnt lgkmcnt(0)
	v_mfma_f32_16x16x32_bf16 v[110:113], v[152:155], v[194:197], v[110:113]
	v_mfma_f32_16x16x32_bf16 v[78:81], v[164:167], v[194:197], v[78:81]
	v_mfma_f32_16x16x32_bf16 v[106:109], v[152:155], v[218:221], v[106:109]
	v_mfma_f32_16x16x32_bf16 v[74:77], v[164:167], v[218:221], v[74:77]
	v_mfma_f32_16x16x32_bf16 v[98:101], v[152:155], v[226:229], v[98:101]
	v_mfma_f32_16x16x32_bf16 v[70:73], v[164:167], v[226:229], v[70:73]
	v_mfma_f32_16x16x32_bf16 v[94:97], v[152:155], v[240:243], v[94:97]
	v_mfma_f32_16x16x32_bf16 v[66:69], v[164:167], v[240:243], v[66:69]
	v_mfma_f32_16x16x32_bf16 v[110:113], v[160:163], v[214:217], v[110:113]
	v_mfma_f32_16x16x32_bf16 v[78:81], v[168:171], v[214:217], v[78:81]
	v_mfma_f32_16x16x32_bf16 v[106:109], v[160:163], v[222:225], v[106:109]
	v_mfma_f32_16x16x32_bf16 v[74:77], v[168:171], v[222:225], v[74:77]
	v_mfma_f32_16x16x32_bf16 v[98:101], v[160:163], v[230:233], v[98:101]
	v_mfma_f32_16x16x32_bf16 v[70:73], v[168:171], v[230:233], v[70:73]
	v_mfma_f32_16x16x32_bf16 v[94:97], v[160:163], v[244:247], v[94:97]
	v_mfma_f32_16x16x32_bf16 v[66:69], v[168:171], v[244:247], v[66:69]
	v_mfma_f32_16x16x32_bf16 v[46:49], v[172:175], v[194:197], v[46:49]
	v_mfma_f32_16x16x32_bf16 v[14:17], v[186:189], v[194:197], v[14:17]
	v_mfma_f32_16x16x32_bf16 v[42:45], v[172:175], v[218:221], v[42:45]
	v_mfma_f32_16x16x32_bf16 v[10:13], v[186:189], v[218:221], v[10:13]
	v_mfma_f32_16x16x32_bf16 v[34:37], v[172:175], v[226:229], v[34:37]
	v_mfma_f32_16x16x32_bf16 v[6:9], v[186:189], v[226:229], v[6:9]
	v_mfma_f32_16x16x32_bf16 v[30:33], v[172:175], v[240:243], v[30:33]
	v_mfma_f32_16x16x32_bf16 v[2:5], v[186:189], v[240:243], v[2:5]
	v_mfma_f32_16x16x32_bf16 v[46:49], v[176:179], v[214:217], v[46:49]
	v_mfma_f32_16x16x32_bf16 v[14:17], v[190:193], v[214:217], v[14:17]
	v_mfma_f32_16x16x32_bf16 v[42:45], v[176:179], v[222:225], v[42:45]
	v_mfma_f32_16x16x32_bf16 v[10:13], v[190:193], v[222:225], v[10:13]
	v_mfma_f32_16x16x32_bf16 v[34:37], v[176:179], v[230:233], v[34:37]
	v_mfma_f32_16x16x32_bf16 v[6:9], v[190:193], v[230:233], v[6:9]
	v_mfma_f32_16x16x32_bf16 v[30:33], v[176:179], v[244:247], v[30:33]
	v_mfma_f32_16x16x32_bf16 v[2:5], v[190:193], v[244:247], v[2:5]
	s_setprio 0
	s_barrier
	s_add_i32 s37, s37, 2
	s_add_u32 s35, s35, 0x100
	s_addc_u32 s36, s36, 0
	s_cmp_gt_u32 s37, 13
	s_mov_b64 s[2:3], s[16:17]
	s_cbranch_scc0 .LBB0_1022
	s_and_b64 vcc, exec, s[42:43]
	s_cbranch_vccz .LBB0_1025
	s_barrier

.LBB0_1041:
	s_add_i32 s23, 0, 0x10000
	s_add_i32 s7, 0, 0x14000
	v_add_u32_e32 v135, s23, v133
	v_add_u32_e32 v147, s7, v133
	ds_read_b128 v[136:139], v135
	ds_read_b128 v[140:143], v135 offset:1024
	ds_read_b128 v[148:151], v135 offset:2048
	ds_read_b128 v[152:155], v135 offset:3072
	ds_read_b128 v[156:159], v147
	ds_read_b128 v[160:163], v147 offset:1024
	ds_read_b128 v[164:167], v147 offset:2048
	ds_read_b128 v[168:171], v147 offset:3072
	s_add_u32 s0, s10, 0x40080
	s_addc_u32 s1, s11, 0
	s_add_i32 s44, s13, 0xc000
	v_lshl_add_u64 v[144:145], s[0:1], 0, v[0:1]
	s_mov_b32 m0, s44
	ds_read_b128 v[172:175], v134
	ds_read_b128 v[176:179], v134 offset:1024
	ds_read_b128 v[186:189], v134 offset:2048
	ds_read_b128 v[190:193], v134 offset:3072
	ds_read_b128 v[194:197], v134 offset:4096
	ds_read_b128 v[214:217], v134 offset:5120
	ds_read_b128 v[218:221], v134 offset:6144
	ds_read_b128 v[222:225], v134 offset:7168
	global_load_lds_dwordx4 v[144:145], off
	v_lshl_add_u64 v[144:145], s[0:1], 0, v[130:131]
	s_add_i32 s0, s13, 0xe000
	s_mov_b32 m0, s0
	s_nop 0
	global_load_lds_dwordx4 v[144:145], off
	s_waitcnt vmcnt(8)
	s_waitcnt lgkmcnt(0)
	s_barrier
	s_setprio 1
	s_waitcnt lgkmcnt(0)
	v_mfma_f32_16x16x32_bf16 v[126:129], v[136:139], v[172:175], v[126:129]
	v_mfma_f32_16x16x32_bf16 v[122:125], v[148:151], v[172:175], v[122:125]
	v_mfma_f32_16x16x32_bf16 v[118:121], v[136:139], v[186:189], v[118:121]
	v_mfma_f32_16x16x32_bf16 v[106:109], v[148:151], v[186:189], v[106:109]
	v_mfma_f32_16x16x32_bf16 v[102:105], v[136:139], v[194:197], v[102:105]
	v_mfma_f32_16x16x32_bf16 v[90:93], v[148:151], v[194:197], v[90:93]
	v_mfma_f32_16x16x32_bf16 v[86:89], v[136:139], v[218:221], v[86:89]
	v_mfma_f32_16x16x32_bf16 v[74:77], v[148:151], v[218:221], v[74:77]
	v_mfma_f32_16x16x32_bf16 v[126:129], v[140:143], v[176:179], v[126:129]
	v_mfma_f32_16x16x32_bf16 v[122:125], v[152:155], v[176:179], v[122:125]
	v_mfma_f32_16x16x32_bf16 v[118:121], v[140:143], v[190:193], v[118:121]
	v_mfma_f32_16x16x32_bf16 v[106:109], v[152:155], v[190:193], v[106:109]
	v_mfma_f32_16x16x32_bf16 v[102:105], v[140:143], v[214:217], v[102:105]
	v_mfma_f32_16x16x32_bf16 v[90:93], v[152:155], v[214:217], v[90:93]
	v_mfma_f32_16x16x32_bf16 v[86:89], v[140:143], v[222:225], v[86:89]
	v_mfma_f32_16x16x32_bf16 v[74:77], v[152:155], v[222:225], v[74:77]
	v_mfma_f32_16x16x32_bf16 v[114:117], v[156:159], v[172:175], v[114:117]
	v_mfma_f32_16x16x32_bf16 v[110:113], v[164:167], v[172:175], v[110:113]
	v_mfma_f32_16x16x32_bf16 v[98:101], v[156:159], v[186:189], v[98:101]
	v_mfma_f32_16x16x32_bf16 v[94:97], v[164:167], v[186:189], v[94:97]
	v_mfma_f32_16x16x32_bf16 v[82:85], v[156:159], v[194:197], v[82:85]
	v_mfma_f32_16x16x32_bf16 v[78:81], v[164:167], v[194:197], v[78:81]
	v_mfma_f32_16x16x32_bf16 v[70:73], v[156:159], v[218:221], v[70:73]
	v_mfma_f32_16x16x32_bf16 v[66:69], v[164:167], v[218:221], v[66:69]
	v_mfma_f32_16x16x32_bf16 v[114:117], v[160:163], v[176:179], v[114:117]
	v_mfma_f32_16x16x32_bf16 v[110:113], v[168:171], v[176:179], v[110:113]
	v_mfma_f32_16x16x32_bf16 v[98:101], v[160:163], v[190:193], v[98:101]
	v_mfma_f32_16x16x32_bf16 v[94:97], v[168:171], v[190:193], v[94:97]
	v_mfma_f32_16x16x32_bf16 v[82:85], v[160:163], v[214:217], v[82:85]
	v_mfma_f32_16x16x32_bf16 v[78:81], v[168:171], v[214:217], v[78:81]
	v_mfma_f32_16x16x32_bf16 v[70:73], v[160:163], v[222:225], v[70:73]
	v_mfma_f32_16x16x32_bf16 v[66:69], v[168:171], v[222:225], v[66:69]
	s_setprio 0
	s_barrier
	v_lshl_add_u64 v[144:145], s[8:9], 0, v[0:1]
	s_mov_b64 s[18:19], 0x100
	s_add_i32 s23, s23, s5
	v_lshl_add_u64 v[180:181], v[144:145], 0, s[18:19]
	s_mov_b32 m0, s23
	s_add_i32 s1, s23, 0x2000
	ds_read_b128 v[172:175], v134 offset:16384
	ds_read_b128 v[176:179], v134 offset:17408
	ds_read_b128 v[186:189], v134 offset:18432
	ds_read_b128 v[190:193], v134 offset:19456
	ds_read_b128 v[194:197], v134 offset:20480
	ds_read_b128 v[214:217], v134 offset:21504
	ds_read_b128 v[218:221], v134 offset:22528
	ds_read_b128 v[222:225], v134 offset:23552
	global_load_lds_dwordx4 v[180:181], off
	v_lshl_add_u64 v[180:181], s[8:9], 0, v[130:131]
	s_add_u32 s42, s8, 0x40100
	v_lshl_add_u64 v[182:183], v[180:181], 0, s[18:19]
	s_mov_b32 m0, s1
	s_addc_u32 s43, s9, 0
	s_add_i32 s7, s7, s5
	global_load_lds_dwordx4 v[182:183], off
	v_lshl_add_u64 v[182:183], s[42:43], 0, v[0:1]
	s_mov_b32 m0, s7
	s_add_i32 s17, s7, 0x2000
	global_load_lds_dwordx4 v[182:183], off
	v_lshl_add_u64 v[182:183], s[42:43], 0, v[130:131]
	s_mov_b32 m0, s17
	s_nop 0
	global_load_lds_dwordx4 v[182:183], off
	v_lshl_add_u64 v[182:183], s[10:11], 0, v[0:1]
	v_lshl_add_u64 v[184:185], v[182:183], 0, s[18:19]
	s_mov_b32 m0, s13
	s_nop 0
	global_load_lds_dwordx4 v[184:185], off
	v_lshl_add_u64 v[184:185], s[10:11], 0, v[130:131]
	v_lshl_add_u64 v[210:211], v[184:185], 0, s[18:19]
	s_mov_b32 m0, s14
	s_nop 0
	global_load_lds_dwordx4 v[210:211], off
	s_waitcnt vmcnt(8)
	s_waitcnt lgkmcnt(0)
	s_barrier
	s_setprio 1
	s_waitcnt lgkmcnt(0)
	v_mfma_f32_16x16x32_bf16 v[62:65], v[136:139], v[172:175], v[62:65]
	v_mfma_f32_16x16x32_bf16 v[58:61], v[148:151], v[172:175], v[58:61]
	v_mfma_f32_16x16x32_bf16 v[54:57], v[136:139], v[186:189], v[54:57]
	v_mfma_f32_16x16x32_bf16 v[50:53], v[148:151], v[186:189], v[50:53]
	v_mfma_f32_16x16x32_bf16 v[38:41], v[136:139], v[194:197], v[38:41]
	v_mfma_f32_16x16x32_bf16 v[34:37], v[148:151], v[194:197], v[34:37]
	v_mfma_f32_16x16x32_bf16 v[22:25], v[136:139], v[218:221], v[22:25]
	v_mfma_f32_16x16x32_bf16 v[18:21], v[148:151], v[218:221], v[18:21]
	v_mfma_f32_16x16x32_bf16 v[62:65], v[140:143], v[176:179], v[62:65]
	v_mfma_f32_16x16x32_bf16 v[58:61], v[152:155], v[176:179], v[58:61]
	v_mfma_f32_16x16x32_bf16 v[54:57], v[140:143], v[190:193], v[54:57]
	v_mfma_f32_16x16x32_bf16 v[50:53], v[152:155], v[190:193], v[50:53]
	v_mfma_f32_16x16x32_bf16 v[38:41], v[140:143], v[214:217], v[38:41]
	v_mfma_f32_16x16x32_bf16 v[34:37], v[152:155], v[214:217], v[34:37]
	v_mfma_f32_16x16x32_bf16 v[22:25], v[140:143], v[222:225], v[22:25]
	v_mfma_f32_16x16x32_bf16 v[18:21], v[152:155], v[222:225], v[18:21]
	v_mfma_f32_16x16x32_bf16 v[46:49], v[156:159], v[172:175], v[46:49]
	v_mfma_f32_16x16x32_bf16 v[42:45], v[164:167], v[172:175], v[42:45]
	v_mfma_f32_16x16x32_bf16 v[30:33], v[156:159], v[186:189], v[30:33]
	v_mfma_f32_16x16x32_bf16 v[26:29], v[164:167], v[186:189], v[26:29]
	v_mfma_f32_16x16x32_bf16 v[14:17], v[156:159], v[194:197], v[14:17]
	v_mfma_f32_16x16x32_bf16 v[10:13], v[164:167], v[194:197], v[10:13]
	v_mfma_f32_16x16x32_bf16 v[6:9], v[156:159], v[218:221], v[6:9]
	v_mfma_f32_16x16x32_bf16 v[2:5], v[164:167], v[218:221], v[2:5]
	v_mfma_f32_16x16x32_bf16 v[46:49], v[160:163], v[176:179], v[46:49]
	v_mfma_f32_16x16x32_bf16 v[42:45], v[168:171], v[176:179], v[42:45]
	v_mfma_f32_16x16x32_bf16 v[30:33], v[160:163], v[190:193], v[30:33]
	v_mfma_f32_16x16x32_bf16 v[26:29], v[168:171], v[190:193], v[26:29]
	v_mfma_f32_16x16x32_bf16 v[14:17], v[160:163], v[214:217], v[14:17]
	v_mfma_f32_16x16x32_bf16 v[10:13], v[168:171], v[214:217], v[10:13]
	v_mfma_f32_16x16x32_bf16 v[6:9], v[160:163], v[222:225], v[6:9]
	v_mfma_f32_16x16x32_bf16 v[2:5], v[168:171], v[222:225], v[2:5]
	s_setprio 0
	s_barrier
	s_add_i32 s46, 0, 0x18000
	s_add_i32 s18, 0, 0x1c000
	v_add_u32_e32 v226, s46, v133
	v_add_u32_e32 v227, s18, v133
	ds_read_b128 v[136:139], v226
	ds_read_b128 v[140:143], v226 offset:1024
	ds_read_b128 v[148:151], v226 offset:2048
	ds_read_b128 v[152:155], v226 offset:3072
	ds_read_b128 v[156:159], v227
	ds_read_b128 v[160:163], v227 offset:1024
	ds_read_b128 v[164:167], v227 offset:2048
	ds_read_b128 v[168:171], v227 offset:3072
	s_add_u32 s42, s10, 0x40100
	s_addc_u32 s43, s11, 0
	s_mov_b32 m0, s30
	v_lshl_add_u64 v[210:211], s[42:43], 0, v[0:1]
	ds_read_b128 v[172:175], v134 offset:32768
	ds_read_b128 v[176:179], v134 offset:33792
	ds_read_b128 v[186:189], v134 offset:34816
	ds_read_b128 v[190:193], v134 offset:35840
	ds_read_b128 v[194:197], v134 offset:36864
	ds_read_b128 v[214:217], v134 offset:37888
	ds_read_b128 v[218:221], v134 offset:38912
	ds_read_b128 v[222:225], v134 offset:39936
	global_load_lds_dwordx4 v[210:211], off
	v_lshl_add_u64 v[210:211], s[42:43], 0, v[130:131]
	s_mov_b32 m0, s31
	s_nop 0
	global_load_lds_dwordx4 v[210:211], off
	s_waitcnt vmcnt(8)
	s_waitcnt lgkmcnt(0)
	s_barrier
	s_setprio 1
	s_waitcnt lgkmcnt(0)
	v_mfma_f32_16x16x32_bf16 v[126:129], v[136:139], v[172:175], v[126:129]
	v_mfma_f32_16x16x32_bf16 v[122:125], v[148:151], v[172:175], v[122:125]
	v_mfma_f32_16x16x32_bf16 v[118:121], v[136:139], v[186:189], v[118:121]
	v_mfma_f32_16x16x32_bf16 v[106:109], v[148:151], v[186:189], v[106:109]
	v_mfma_f32_16x16x32_bf16 v[102:105], v[136:139], v[194:197], v[102:105]
	v_mfma_f32_16x16x32_bf16 v[90:93], v[148:151], v[194:197], v[90:93]
	v_mfma_f32_16x16x32_bf16 v[86:89], v[136:139], v[218:221], v[86:89]
	v_mfma_f32_16x16x32_bf16 v[74:77], v[148:151], v[218:221], v[74:77]
	v_mfma_f32_16x16x32_bf16 v[126:129], v[140:143], v[176:179], v[126:129]
	v_mfma_f32_16x16x32_bf16 v[122:125], v[152:155], v[176:179], v[122:125]
	v_mfma_f32_16x16x32_bf16 v[118:121], v[140:143], v[190:193], v[118:121]
	v_mfma_f32_16x16x32_bf16 v[106:109], v[152:155], v[190:193], v[106:109]
	v_mfma_f32_16x16x32_bf16 v[102:105], v[140:143], v[214:217], v[102:105]
	v_mfma_f32_16x16x32_bf16 v[90:93], v[152:155], v[214:217], v[90:93]
	v_mfma_f32_16x16x32_bf16 v[86:89], v[140:143], v[222:225], v[86:89]
	v_mfma_f32_16x16x32_bf16 v[74:77], v[152:155], v[222:225], v[74:77]
	v_mfma_f32_16x16x32_bf16 v[114:117], v[156:159], v[172:175], v[114:117]
	v_mfma_f32_16x16x32_bf16 v[110:113], v[164:167], v[172:175], v[110:113]
	v_mfma_f32_16x16x32_bf16 v[98:101], v[156:159], v[186:189], v[98:101]
	v_mfma_f32_16x16x32_bf16 v[94:97], v[164:167], v[186:189], v[94:97]
	v_mfma_f32_16x16x32_bf16 v[82:85], v[156:159], v[194:197], v[82:85]
	v_mfma_f32_16x16x32_bf16 v[78:81], v[164:167], v[194:197], v[78:81]
	v_mfma_f32_16x16x32_bf16 v[70:73], v[156:159], v[218:221], v[70:73]
	v_mfma_f32_16x16x32_bf16 v[66:69], v[164:167], v[218:221], v[66:69]
	v_mfma_f32_16x16x32_bf16 v[114:117], v[160:163], v[176:179], v[114:117]
	v_mfma_f32_16x16x32_bf16 v[110:113], v[168:171], v[176:179], v[110:113]
	v_mfma_f32_16x16x32_bf16 v[98:101], v[160:163], v[190:193], v[98:101]
	v_mfma_f32_16x16x32_bf16 v[94:97], v[168:171], v[190:193], v[94:97]
	v_mfma_f32_16x16x32_bf16 v[82:85], v[160:163], v[214:217], v[82:85]
	v_mfma_f32_16x16x32_bf16 v[78:81], v[168:171], v[214:217], v[78:81]
	v_mfma_f32_16x16x32_bf16 v[70:73], v[160:163], v[222:225], v[70:73]
	v_mfma_f32_16x16x32_bf16 v[66:69], v[168:171], v[222:225], v[66:69]
	s_setprio 0
	s_barrier
	s_add_i32 s46, s46, s5
	s_mov_b64 s[50:51], 0x180
	s_add_i32 s42, s46, 0x2000
	v_lshl_add_u64 v[144:145], v[144:145], 0, s[50:51]
	s_mov_b32 m0, s46
	s_add_u32 s48, s8, 0x40180
	ds_read_b128 v[172:175], v134 offset:49152
	ds_read_b128 v[176:179], v134 offset:50176
	ds_read_b128 v[186:189], v134 offset:51200
	ds_read_b128 v[190:193], v134 offset:52224
	ds_read_b128 v[194:197], v134 offset:53248
	ds_read_b128 v[214:217], v134 offset:54272
	ds_read_b128 v[218:221], v134 offset:55296
	ds_read_b128 v[222:225], v134 offset:56320
	global_load_lds_dwordx4 v[144:145], off
	v_lshl_add_u64 v[144:145], v[180:181], 0, s[50:51]
	s_mov_b32 m0, s42
	s_addc_u32 s49, s9, 0
	s_add_i32 s43, s18, s5
	global_load_lds_dwordx4 v[144:145], off
	v_lshl_add_u64 v[144:145], s[48:49], 0, v[0:1]
	s_mov_b32 m0, s43
	s_add_i32 s45, s43, 0x2000
	global_load_lds_dwordx4 v[144:145], off
	v_lshl_add_u64 v[144:145], s[48:49], 0, v[130:131]
	s_mov_b32 m0, s45
	s_nop 0
	global_load_lds_dwordx4 v[144:145], off
	v_lshl_add_u64 v[144:145], v[182:183], 0, s[50:51]
	s_mov_b32 m0, s35
	s_nop 0
	global_load_lds_dwordx4 v[144:145], off
	v_lshl_add_u64 v[144:145], v[184:185], 0, s[50:51]
	s_mov_b32 m0, s36
	s_nop 0
	global_load_lds_dwordx4 v[144:145], off
	s_waitcnt vmcnt(8)
	s_waitcnt lgkmcnt(0)
	s_barrier
	s_setprio 1
	s_waitcnt lgkmcnt(0)
	v_mfma_f32_16x16x32_bf16 v[62:65], v[136:139], v[172:175], v[62:65]
	v_mfma_f32_16x16x32_bf16 v[58:61], v[148:151], v[172:175], v[58:61]
	v_mfma_f32_16x16x32_bf16 v[54:57], v[136:139], v[186:189], v[54:57]
	v_mfma_f32_16x16x32_bf16 v[50:53], v[148:151], v[186:189], v[50:53]
	v_mfma_f32_16x16x32_bf16 v[38:41], v[136:139], v[194:197], v[38:41]
	v_mfma_f32_16x16x32_bf16 v[34:37], v[148:151], v[194:197], v[34:37]
	v_mfma_f32_16x16x32_bf16 v[22:25], v[136:139], v[218:221], v[22:25]
	v_mfma_f32_16x16x32_bf16 v[18:21], v[148:151], v[218:221], v[18:21]
	v_mfma_f32_16x16x32_bf16 v[62:65], v[140:143], v[176:179], v[62:65]
	v_mfma_f32_16x16x32_bf16 v[58:61], v[152:155], v[176:179], v[58:61]
	v_mfma_f32_16x16x32_bf16 v[54:57], v[140:143], v[190:193], v[54:57]
	v_mfma_f32_16x16x32_bf16 v[50:53], v[152:155], v[190:193], v[50:53]
	v_mfma_f32_16x16x32_bf16 v[38:41], v[140:143], v[214:217], v[38:41]
	v_mfma_f32_16x16x32_bf16 v[34:37], v[152:155], v[214:217], v[34:37]
	v_mfma_f32_16x16x32_bf16 v[22:25], v[140:143], v[222:225], v[22:25]
	v_mfma_f32_16x16x32_bf16 v[18:21], v[152:155], v[222:225], v[18:21]
	v_mfma_f32_16x16x32_bf16 v[46:49], v[156:159], v[172:175], v[46:49]
	v_mfma_f32_16x16x32_bf16 v[42:45], v[164:167], v[172:175], v[42:45]
	v_mfma_f32_16x16x32_bf16 v[30:33], v[156:159], v[186:189], v[30:33]
	v_mfma_f32_16x16x32_bf16 v[26:29], v[164:167], v[186:189], v[26:29]
	v_mfma_f32_16x16x32_bf16 v[14:17], v[156:159], v[194:197], v[14:17]
	v_mfma_f32_16x16x32_bf16 v[10:13], v[164:167], v[194:197], v[10:13]
	v_mfma_f32_16x16x32_bf16 v[6:9], v[156:159], v[218:221], v[6:9]
	v_mfma_f32_16x16x32_bf16 v[2:5], v[164:167], v[218:221], v[2:5]
	v_mfma_f32_16x16x32_bf16 v[46:49], v[160:163], v[176:179], v[46:49]
	v_mfma_f32_16x16x32_bf16 v[42:45], v[168:171], v[176:179], v[42:45]
	v_mfma_f32_16x16x32_bf16 v[30:33], v[160:163], v[190:193], v[30:33]
	v_mfma_f32_16x16x32_bf16 v[26:29], v[168:171], v[190:193], v[26:29]
	v_mfma_f32_16x16x32_bf16 v[14:17], v[160:163], v[214:217], v[14:17]
	v_mfma_f32_16x16x32_bf16 v[10:13], v[168:171], v[214:217], v[10:13]
	v_mfma_f32_16x16x32_bf16 v[6:9], v[160:163], v[222:225], v[6:9]
	v_mfma_f32_16x16x32_bf16 v[2:5], v[168:171], v[222:225], v[2:5]
	s_setprio 0
	s_barrier
	ds_read_b128 v[136:139], v135
	ds_read_b128 v[140:143], v135 offset:1024
	ds_read_b128 v[148:151], v135 offset:2048
	ds_read_b128 v[152:155], v135 offset:3072
	ds_read_b128 v[156:159], v147
	ds_read_b128 v[160:163], v147 offset:1024
	ds_read_b128 v[164:167], v147 offset:2048
	ds_read_b128 v[168:171], v147 offset:3072
	s_add_u32 s48, s10, 0x40180
	s_addc_u32 s49, s11, 0
	s_mov_b32 m0, s44
	v_lshl_add_u64 v[144:145], s[48:49], 0, v[0:1]
	ds_read_b128 v[172:175], v134
	ds_read_b128 v[176:179], v134 offset:1024
	ds_read_b128 v[186:189], v134 offset:2048
	ds_read_b128 v[190:193], v134 offset:3072
	ds_read_b128 v[194:197], v134 offset:4096
	ds_read_b128 v[214:217], v134 offset:5120
	ds_read_b128 v[218:221], v134 offset:6144
	ds_read_b128 v[222:225], v134 offset:7168
	global_load_lds_dwordx4 v[144:145], off
	v_lshl_add_u64 v[144:145], s[48:49], 0, v[130:131]
	s_mov_b32 m0, s0
	s_nop 0
	global_load_lds_dwordx4 v[144:145], off
	s_waitcnt vmcnt(8)
	s_waitcnt lgkmcnt(0)
	s_barrier
	s_setprio 1
	s_waitcnt lgkmcnt(0)
	v_mfma_f32_16x16x32_bf16 v[126:129], v[136:139], v[172:175], v[126:129]
	v_mfma_f32_16x16x32_bf16 v[122:125], v[148:151], v[172:175], v[122:125]
	v_mfma_f32_16x16x32_bf16 v[118:121], v[136:139], v[186:189], v[118:121]
	v_mfma_f32_16x16x32_bf16 v[106:109], v[148:151], v[186:189], v[106:109]
	v_mfma_f32_16x16x32_bf16 v[102:105], v[136:139], v[194:197], v[102:105]
	v_mfma_f32_16x16x32_bf16 v[90:93], v[148:151], v[194:197], v[90:93]
	v_mfma_f32_16x16x32_bf16 v[86:89], v[136:139], v[218:221], v[86:89]
	v_mfma_f32_16x16x32_bf16 v[74:77], v[148:151], v[218:221], v[74:77]
	v_mfma_f32_16x16x32_bf16 v[126:129], v[140:143], v[176:179], v[126:129]
	v_mfma_f32_16x16x32_bf16 v[122:125], v[152:155], v[176:179], v[122:125]
	v_mfma_f32_16x16x32_bf16 v[118:121], v[140:143], v[190:193], v[118:121]
	v_mfma_f32_16x16x32_bf16 v[106:109], v[152:155], v[190:193], v[106:109]
	v_mfma_f32_16x16x32_bf16 v[102:105], v[140:143], v[214:217], v[102:105]
	v_mfma_f32_16x16x32_bf16 v[90:93], v[152:155], v[214:217], v[90:93]
	v_mfma_f32_16x16x32_bf16 v[86:89], v[140:143], v[222:225], v[86:89]
	v_mfma_f32_16x16x32_bf16 v[74:77], v[152:155], v[222:225], v[74:77]
	v_mfma_f32_16x16x32_bf16 v[114:117], v[156:159], v[172:175], v[114:117]
	v_mfma_f32_16x16x32_bf16 v[110:113], v[164:167], v[172:175], v[110:113]
	v_mfma_f32_16x16x32_bf16 v[98:101], v[156:159], v[186:189], v[98:101]
	v_mfma_f32_16x16x32_bf16 v[94:97], v[164:167], v[186:189], v[94:97]
	v_mfma_f32_16x16x32_bf16 v[82:85], v[156:159], v[194:197], v[82:85]
	v_mfma_f32_16x16x32_bf16 v[78:81], v[164:167], v[194:197], v[78:81]
	v_mfma_f32_16x16x32_bf16 v[70:73], v[156:159], v[218:221], v[70:73]
	v_mfma_f32_16x16x32_bf16 v[66:69], v[164:167], v[218:221], v[66:69]
	v_mfma_f32_16x16x32_bf16 v[114:117], v[160:163], v[176:179], v[114:117]
	v_mfma_f32_16x16x32_bf16 v[110:113], v[168:171], v[176:179], v[110:113]
	v_mfma_f32_16x16x32_bf16 v[98:101], v[160:163], v[190:193], v[98:101]
	v_mfma_f32_16x16x32_bf16 v[94:97], v[168:171], v[190:193], v[94:97]
	v_mfma_f32_16x16x32_bf16 v[82:85], v[160:163], v[214:217], v[82:85]
	v_mfma_f32_16x16x32_bf16 v[78:81], v[168:171], v[214:217], v[78:81]
	v_mfma_f32_16x16x32_bf16 v[70:73], v[160:163], v[222:225], v[70:73]
	v_mfma_f32_16x16x32_bf16 v[66:69], v[168:171], v[222:225], v[66:69]
	s_setprio 0
	s_barrier
	s_mov_b32 m0, s23
	v_lshl_add_u64 v[144:145], s[28:29], 0, v[0:1]
	s_add_u32 s0, s28, 0x40000
	ds_read_b128 v[172:175], v134 offset:16384
	ds_read_b128 v[176:179], v134 offset:17408
	ds_read_b128 v[186:189], v134 offset:18432
	ds_read_b128 v[190:193], v134 offset:19456
	ds_read_b128 v[194:197], v134 offset:20480
	ds_read_b128 v[214:217], v134 offset:21504
	ds_read_b128 v[218:221], v134 offset:22528
	ds_read_b128 v[222:225], v134 offset:23552
	global_load_lds_dwordx4 v[144:145], off
	v_lshl_add_u64 v[180:181], s[28:29], 0, v[130:131]
	s_mov_b32 m0, s1
	s_addc_u32 s1, s29, 0
	global_load_lds_dwordx4 v[180:181], off
	v_lshl_add_u64 v[182:183], s[0:1], 0, v[0:1]
	s_mov_b32 m0, s7
	v_lshl_add_u64 v[184:185], s[26:27], 0, v[130:131]
	global_load_lds_dwordx4 v[182:183], off
	v_lshl_add_u64 v[182:183], s[0:1], 0, v[130:131]
	s_mov_b32 m0, s17
	s_nop 0
	global_load_lds_dwordx4 v[182:183], off
	v_lshl_add_u64 v[182:183], s[26:27], 0, v[0:1]
	s_mov_b32 m0, s13
	s_nop 0
	global_load_lds_dwordx4 v[182:183], off
	s_mov_b32 m0, s14
	s_nop 0
	global_load_lds_dwordx4 v[184:185], off
	s_waitcnt vmcnt(8)
	s_waitcnt lgkmcnt(0)
	s_barrier
	s_setprio 1
	s_waitcnt lgkmcnt(0)
	v_mfma_f32_16x16x32_bf16 v[62:65], v[136:139], v[172:175], v[62:65]
	v_mfma_f32_16x16x32_bf16 v[58:61], v[148:151], v[172:175], v[58:61]
	v_mfma_f32_16x16x32_bf16 v[54:57], v[136:139], v[186:189], v[54:57]
	v_mfma_f32_16x16x32_bf16 v[50:53], v[148:151], v[186:189], v[50:53]
	v_mfma_f32_16x16x32_bf16 v[38:41], v[136:139], v[194:197], v[38:41]
	v_mfma_f32_16x16x32_bf16 v[34:37], v[148:151], v[194:197], v[34:37]
	v_mfma_f32_16x16x32_bf16 v[22:25], v[136:139], v[218:221], v[22:25]
	v_mfma_f32_16x16x32_bf16 v[18:21], v[148:151], v[218:221], v[18:21]
	v_mfma_f32_16x16x32_bf16 v[62:65], v[140:143], v[176:179], v[62:65]
	v_mfma_f32_16x16x32_bf16 v[58:61], v[152:155], v[176:179], v[58:61]
	v_mfma_f32_16x16x32_bf16 v[54:57], v[140:143], v[190:193], v[54:57]
	v_mfma_f32_16x16x32_bf16 v[50:53], v[152:155], v[190:193], v[50:53]
	v_mfma_f32_16x16x32_bf16 v[38:41], v[140:143], v[214:217], v[38:41]
	v_mfma_f32_16x16x32_bf16 v[34:37], v[152:155], v[214:217], v[34:37]
	v_mfma_f32_16x16x32_bf16 v[22:25], v[140:143], v[222:225], v[22:25]
	v_mfma_f32_16x16x32_bf16 v[18:21], v[152:155], v[222:225], v[18:21]
	v_mfma_f32_16x16x32_bf16 v[46:49], v[156:159], v[172:175], v[46:49]
	v_mfma_f32_16x16x32_bf16 v[42:45], v[164:167], v[172:175], v[42:45]
	v_mfma_f32_16x16x32_bf16 v[30:33], v[156:159], v[186:189], v[30:33]
	v_mfma_f32_16x16x32_bf16 v[26:29], v[164:167], v[186:189], v[26:29]
	v_mfma_f32_16x16x32_bf16 v[14:17], v[156:159], v[194:197], v[14:17]
	v_mfma_f32_16x16x32_bf16 v[10:13], v[164:167], v[194:197], v[10:13]
	v_mfma_f32_16x16x32_bf16 v[6:9], v[156:159], v[218:221], v[6:9]
	v_mfma_f32_16x16x32_bf16 v[2:5], v[164:167], v[218:221], v[2:5]
	v_mfma_f32_16x16x32_bf16 v[46:49], v[160:163], v[176:179], v[46:49]
	v_mfma_f32_16x16x32_bf16 v[42:45], v[168:171], v[176:179], v[42:45]
	v_mfma_f32_16x16x32_bf16 v[30:33], v[160:163], v[190:193], v[30:33]
	v_mfma_f32_16x16x32_bf16 v[26:29], v[168:171], v[190:193], v[26:29]
	v_mfma_f32_16x16x32_bf16 v[14:17], v[160:163], v[214:217], v[14:17]
	v_mfma_f32_16x16x32_bf16 v[10:13], v[168:171], v[214:217], v[10:13]
	v_mfma_f32_16x16x32_bf16 v[6:9], v[160:163], v[222:225], v[6:9]
	v_mfma_f32_16x16x32_bf16 v[2:5], v[168:171], v[222:225], v[2:5]
	s_setprio 0
	s_barrier
	ds_read_b128 v[136:139], v226
	ds_read_b128 v[140:143], v226 offset:1024
	ds_read_b128 v[148:151], v226 offset:2048
	ds_read_b128 v[152:155], v226 offset:3072
	ds_read_b128 v[156:159], v227
	ds_read_b128 v[160:163], v227 offset:1024
	ds_read_b128 v[164:167], v227 offset:2048
	ds_read_b128 v[168:171], v227 offset:3072
	s_add_u32 s0, s26, 0x40000
	s_addc_u32 s1, s27, 0
	s_mov_b32 m0, s30
	v_lshl_add_u64 v[210:211], s[0:1], 0, v[0:1]
	ds_read_b128 v[172:175], v134 offset:32768
	ds_read_b128 v[176:179], v134 offset:33792
	ds_read_b128 v[186:189], v134 offset:34816
	ds_read_b128 v[190:193], v134 offset:35840
	ds_read_b128 v[194:197], v134 offset:36864
	ds_read_b128 v[214:217], v134 offset:37888
	ds_read_b128 v[218:221], v134 offset:38912
	ds_read_b128 v[222:225], v134 offset:39936
	global_load_lds_dwordx4 v[210:211], off
	v_lshl_add_u64 v[210:211], s[0:1], 0, v[130:131]
	s_mov_b32 m0, s31
	s_nop 0
	global_load_lds_dwordx4 v[210:211], off
	s_waitcnt vmcnt(8)
	s_waitcnt lgkmcnt(0)
	s_barrier
	s_setprio 1
	s_waitcnt lgkmcnt(0)
	v_mfma_f32_16x16x32_bf16 v[126:129], v[136:139], v[172:175], v[126:129]
	v_mfma_f32_16x16x32_bf16 v[122:125], v[148:151], v[172:175], v[122:125]
	v_mfma_f32_16x16x32_bf16 v[118:121], v[136:139], v[186:189], v[118:121]
	v_mfma_f32_16x16x32_bf16 v[106:109], v[148:151], v[186:189], v[106:109]
	v_mfma_f32_16x16x32_bf16 v[102:105], v[136:139], v[194:197], v[102:105]
	v_mfma_f32_16x16x32_bf16 v[90:93], v[148:151], v[194:197], v[90:93]
	v_mfma_f32_16x16x32_bf16 v[86:89], v[136:139], v[218:221], v[86:89]
	v_mfma_f32_16x16x32_bf16 v[74:77], v[148:151], v[218:221], v[74:77]
	v_mfma_f32_16x16x32_bf16 v[126:129], v[140:143], v[176:179], v[126:129]
	v_mfma_f32_16x16x32_bf16 v[122:125], v[152:155], v[176:179], v[122:125]
	v_mfma_f32_16x16x32_bf16 v[118:121], v[140:143], v[190:193], v[118:121]
	v_mfma_f32_16x16x32_bf16 v[106:109], v[152:155], v[190:193], v[106:109]
	v_mfma_f32_16x16x32_bf16 v[102:105], v[140:143], v[214:217], v[102:105]
	v_mfma_f32_16x16x32_bf16 v[90:93], v[152:155], v[214:217], v[90:93]
	v_mfma_f32_16x16x32_bf16 v[86:89], v[140:143], v[222:225], v[86:89]
	v_mfma_f32_16x16x32_bf16 v[74:77], v[152:155], v[222:225], v[74:77]
	v_mfma_f32_16x16x32_bf16 v[114:117], v[156:159], v[172:175], v[114:117]
	v_mfma_f32_16x16x32_bf16 v[110:113], v[164:167], v[172:175], v[110:113]
	v_mfma_f32_16x16x32_bf16 v[98:101], v[156:159], v[186:189], v[98:101]
	v_mfma_f32_16x16x32_bf16 v[94:97], v[164:167], v[186:189], v[94:97]
	v_mfma_f32_16x16x32_bf16 v[82:85], v[156:159], v[194:197], v[82:85]
	v_mfma_f32_16x16x32_bf16 v[78:81], v[164:167], v[194:197], v[78:81]
	v_mfma_f32_16x16x32_bf16 v[70:73], v[156:159], v[218:221], v[70:73]
	v_mfma_f32_16x16x32_bf16 v[66:69], v[164:167], v[218:221], v[66:69]
	v_mfma_f32_16x16x32_bf16 v[114:117], v[160:163], v[176:179], v[114:117]
	v_mfma_f32_16x16x32_bf16 v[110:113], v[168:171], v[176:179], v[110:113]
	v_mfma_f32_16x16x32_bf16 v[98:101], v[160:163], v[190:193], v[98:101]
	v_mfma_f32_16x16x32_bf16 v[94:97], v[168:171], v[190:193], v[94:97]
	v_mfma_f32_16x16x32_bf16 v[82:85], v[160:163], v[214:217], v[82:85]
	v_mfma_f32_16x16x32_bf16 v[78:81], v[168:171], v[214:217], v[78:81]
	v_mfma_f32_16x16x32_bf16 v[70:73], v[160:163], v[222:225], v[70:73]
	v_mfma_f32_16x16x32_bf16 v[66:69], v[168:171], v[222:225], v[66:69]
	s_setprio 0
	s_barrier
	s_mov_b32 m0, s46
	v_lshl_add_u64 v[144:145], v[144:145], 0, s[54:55]
	s_add_u32 s0, s28, 0x40080
	ds_read_b128 v[172:175], v134 offset:49152
	ds_read_b128 v[176:179], v134 offset:50176
	ds_read_b128 v[186:189], v134 offset:51200
	ds_read_b128 v[190:193], v134 offset:52224
	ds_read_b128 v[194:197], v134 offset:53248
	ds_read_b128 v[214:217], v134 offset:54272
	ds_read_b128 v[218:221], v134 offset:55296
	ds_read_b128 v[222:225], v134 offset:56320
	global_load_lds_dwordx4 v[144:145], off
	v_lshl_add_u64 v[144:145], v[180:181], 0, s[54:55]
	s_mov_b32 m0, s42
	s_addc_u32 s1, s29, 0
	global_load_lds_dwordx4 v[144:145], off
	v_lshl_add_u64 v[144:145], s[0:1], 0, v[0:1]
	s_mov_b32 m0, s43
	s_nop 0
	global_load_lds_dwordx4 v[144:145], off
	v_lshl_add_u64 v[144:145], s[0:1], 0, v[130:131]
	s_mov_b32 m0, s45
	s_nop 0
	global_load_lds_dwordx4 v[144:145], off
	v_lshl_add_u64 v[144:145], v[182:183], 0, s[54:55]
	s_mov_b32 m0, s35
	s_nop 0
	global_load_lds_dwordx4 v[144:145], off
	v_lshl_add_u64 v[144:145], v[184:185], 0, s[54:55]
	s_mov_b32 m0, s36
	s_nop 0
	global_load_lds_dwordx4 v[144:145], off
	s_waitcnt vmcnt(8)
	s_waitcnt lgkmcnt(0)
	s_barrier
	s_setprio 1
	s_waitcnt lgkmcnt(0)
	v_mfma_f32_16x16x32_bf16 v[62:65], v[136:139], v[172:175], v[62:65]
	v_mfma_f32_16x16x32_bf16 v[58:61], v[148:151], v[172:175], v[58:61]
	v_mfma_f32_16x16x32_bf16 v[54:57], v[136:139], v[186:189], v[54:57]
	v_mfma_f32_16x16x32_bf16 v[50:53], v[148:151], v[186:189], v[50:53]
	v_mfma_f32_16x16x32_bf16 v[38:41], v[136:139], v[194:197], v[38:41]
	v_mfma_f32_16x16x32_bf16 v[34:37], v[148:151], v[194:197], v[34:37]
	v_mfma_f32_16x16x32_bf16 v[22:25], v[136:139], v[218:221], v[22:25]
	v_mfma_f32_16x16x32_bf16 v[18:21], v[148:151], v[218:221], v[18:21]
	v_mfma_f32_16x16x32_bf16 v[62:65], v[140:143], v[176:179], v[62:65]
	v_mfma_f32_16x16x32_bf16 v[58:61], v[152:155], v[176:179], v[58:61]
	v_mfma_f32_16x16x32_bf16 v[54:57], v[140:143], v[190:193], v[54:57]
	v_mfma_f32_16x16x32_bf16 v[50:53], v[152:155], v[190:193], v[50:53]
	v_mfma_f32_16x16x32_bf16 v[38:41], v[140:143], v[214:217], v[38:41]
	v_mfma_f32_16x16x32_bf16 v[34:37], v[152:155], v[214:217], v[34:37]
	v_mfma_f32_16x16x32_bf16 v[22:25], v[140:143], v[222:225], v[22:25]
	v_mfma_f32_16x16x32_bf16 v[18:21], v[152:155], v[222:225], v[18:21]
	v_mfma_f32_16x16x32_bf16 v[46:49], v[156:159], v[172:175], v[46:49]
	v_mfma_f32_16x16x32_bf16 v[42:45], v[164:167], v[172:175], v[42:45]
	v_mfma_f32_16x16x32_bf16 v[30:33], v[156:159], v[186:189], v[30:33]
	v_mfma_f32_16x16x32_bf16 v[26:29], v[164:167], v[186:189], v[26:29]
	v_mfma_f32_16x16x32_bf16 v[14:17], v[156:159], v[194:197], v[14:17]
	v_mfma_f32_16x16x32_bf16 v[10:13], v[164:167], v[194:197], v[10:13]
	v_mfma_f32_16x16x32_bf16 v[6:9], v[156:159], v[218:221], v[6:9]
	v_mfma_f32_16x16x32_bf16 v[2:5], v[164:167], v[218:221], v[2:5]
	v_mfma_f32_16x16x32_bf16 v[46:49], v[160:163], v[176:179], v[46:49]
	v_mfma_f32_16x16x32_bf16 v[42:45], v[168:171], v[176:179], v[42:45]
	v_mfma_f32_16x16x32_bf16 v[30:33], v[160:163], v[190:193], v[30:33]
	v_mfma_f32_16x16x32_bf16 v[26:29], v[168:171], v[190:193], v[26:29]
	v_mfma_f32_16x16x32_bf16 v[14:17], v[160:163], v[214:217], v[14:17]
	v_mfma_f32_16x16x32_bf16 v[10:13], v[168:171], v[214:217], v[10:13]
	v_mfma_f32_16x16x32_bf16 v[6:9], v[160:163], v[222:225], v[6:9]
	v_mfma_f32_16x16x32_bf16 v[2:5], v[168:171], v[222:225], v[2:5]
	s_setprio 0
	s_barrier
	s_and_b64 vcc, exec, s[38:39]
	s_cbranch_vccnz .LBB0_1034
	s_nop 3
	v_mov_b32_e32 v2, 0
	s_mov_b32 s2, s6
	s_mov_b32 s37, s22
	s_mov_b32 s4, s16
	s_mov_b64 s[8:9], s[28:29]
	s_mov_b64 s[10:11], s[26:27]
	s_mov_b32 s40, s41
	v_mov_b32_e32 v3, v2
	v_mov_b32_e32 v4, v2
	v_mov_b32_e32 v5, v2
	v_mov_b32_e32 v6, v2
	v_mov_b32_e32 v7, v2
	v_mov_b32_e32 v8, v2
	v_mov_b32_e32 v9, v2
	v_mov_b32_e32 v10, v2
	v_mov_b32_e32 v11, v2
	v_mov_b32_e32 v12, v2
	v_mov_b32_e32 v13, v2
	v_mov_b32_e32 v14, v2
	v_mov_b32_e32 v15, v2
	v_mov_b32_e32 v16, v2
	v_mov_b32_e32 v17, v2
	v_mov_b32_e32 v26, v2
	v_mov_b32_e32 v27, v2
	v_mov_b32_e32 v28, v2
	v_mov_b32_e32 v29, v2
	v_mov_b32_e32 v30, v2
	v_mov_b32_e32 v31, v2
	v_mov_b32_e32 v32, v2
	v_mov_b32_e32 v33, v2
	v_mov_b32_e32 v42, v2
	v_mov_b32_e32 v43, v2
	v_mov_b32_e32 v44, v2
	v_mov_b32_e32 v45, v2
	v_mov_b32_e32 v46, v2
	v_mov_b32_e32 v47, v2
	v_mov_b32_e32 v48, v2
	v_mov_b32_e32 v49, v2
	v_mov_b32_e32 v18, v2
	v_mov_b32_e32 v19, v2
	v_mov_b32_e32 v20, v2
	v_mov_b32_e32 v21, v2
	v_mov_b32_e32 v22, v2
	v_mov_b32_e32 v23, v2
	v_mov_b32_e32 v24, v2
	v_mov_b32_e32 v25, v2
	v_mov_b32_e32 v34, v2
	v_mov_b32_e32 v35, v2
	v_mov_b32_e32 v36, v2
	v_mov_b32_e32 v37, v2
	v_mov_b32_e32 v38, v2
	v_mov_b32_e32 v39, v2
	v_mov_b32_e32 v40, v2
	v_mov_b32_e32 v41, v2
	v_mov_b32_e32 v50, v2
	v_mov_b32_e32 v51, v2
	v_mov_b32_e32 v52, v2
	v_mov_b32_e32 v53, v2
	v_mov_b32_e32 v54, v2
	v_mov_b32_e32 v55, v2
	v_mov_b32_e32 v56, v2
	v_mov_b32_e32 v57, v2
	v_mov_b32_e32 v58, v2
	v_mov_b32_e32 v59, v2
	v_mov_b32_e32 v60, v2
	v_mov_b32_e32 v61, v2
	v_mov_b32_e32 v62, v2
	v_mov_b32_e32 v63, v2
	v_mov_b32_e32 v64, v2
	v_mov_b32_e32 v65, v2
	v_mov_b32_e32 v66, v2
	v_mov_b32_e32 v67, v2
	v_mov_b32_e32 v68, v2
	v_mov_b32_e32 v69, v2
	v_mov_b32_e32 v70, v2
	v_mov_b32_e32 v71, v2
	v_mov_b32_e32 v72, v2
	v_mov_b32_e32 v73, v2
	v_mov_b32_e32 v78, v2
	v_mov_b32_e32 v79, v2
	v_mov_b32_e32 v80, v2
	v_mov_b32_e32 v81, v2
	v_mov_b32_e32 v82, v2
	v_mov_b32_e32 v83, v2
	v_mov_b32_e32 v84, v2
	v_mov_b32_e32 v85, v2
	v_mov_b32_e32 v94, v2
	v_mov_b32_e32 v95, v2
	v_mov_b32_e32 v96, v2
	v_mov_b32_e32 v97, v2
	v_mov_b32_e32 v98, v2
	v_mov_b32_e32 v99, v2
	v_mov_b32_e32 v100, v2
	v_mov_b32_e32 v101, v2
	v_mov_b32_e32 v110, v2
	v_mov_b32_e32 v111, v2
	v_mov_b32_e32 v112, v2
	v_mov_b32_e32 v113, v2
	v_mov_b32_e32 v114, v2
	v_mov_b32_e32 v115, v2
	v_mov_b32_e32 v116, v2
	v_mov_b32_e32 v117, v2
	v_mov_b32_e32 v74, v2
	v_mov_b32_e32 v75, v2
	v_mov_b32_e32 v76, v2
	v_mov_b32_e32 v77, v2
	v_mov_b32_e32 v86, v2
	v_mov_b32_e32 v87, v2
	v_mov_b32_e32 v88, v2
	v_mov_b32_e32 v89, v2
	v_mov_b32_e32 v90, v2
	v_mov_b32_e32 v91, v2
	v_mov_b32_e32 v92, v2
	v_mov_b32_e32 v93, v2
	v_mov_b32_e32 v102, v2
	v_mov_b32_e32 v103, v2
	v_mov_b32_e32 v104, v2
	v_mov_b32_e32 v105, v2
	v_mov_b32_e32 v106, v2
	v_mov_b32_e32 v107, v2
	v_mov_b32_e32 v108, v2
	v_mov_b32_e32 v109, v2
	v_mov_b32_e32 v118, v2
	v_mov_b32_e32 v119, v2
	v_mov_b32_e32 v120, v2
	v_mov_b32_e32 v121, v2
	v_mov_b32_e32 v122, v2
	v_mov_b32_e32 v123, v2
	v_mov_b32_e32 v124, v2
	v_mov_b32_e32 v125, v2
	v_mov_b32_e32 v126, v2
	v_mov_b32_e32 v127, v2
	v_mov_b32_e32 v128, v2
	v_mov_b32_e32 v129, v2
	s_branch .LBB0_1034

.LBB0_1171:
	s_add_u32 s8, s6, 0xfffc0080
	s_addc_u32 s9, s7, -1
	s_add_i32 s18, 0, 0x10000
	s_cmp_eq_u32 s49, 12
	s_cselect_b32 s11, s0, s9
	s_cselect_b32 s10, s1, s8
	v_add_u32_e32 v144, s18, v147
	s_cselect_b32 s9, s12, s37
	s_cselect_b32 s8, s13, s36
	s_add_i32 s19, 0, 0x14000
	ds_read_b128 v[140:143], v144
	ds_read_b128 v[150:153], v144 offset:1024
	ds_read_b128 v[154:157], v144 offset:2048
	ds_read_b128 v[158:161], v144 offset:3072
	v_add_u32_e32 v144, s19, v147
	ds_read_b128 v[162:165], v144
	ds_read_b128 v[166:169], v144 offset:1024
	ds_read_b128 v[170:173], v144 offset:2048
	ds_read_b128 v[174:177], v144 offset:3072
	v_lshl_add_u64 v[144:145], s[6:7], 0, v[136:137]
	s_add_i32 m0, s3, 0xc000
	ds_read_b128 v[178:181], v149
	ds_read_b128 v[186:189], v149 offset:1024
	ds_read_b128 v[190:193], v149 offset:2048
	ds_read_b128 v[194:197], v149 offset:3072
	ds_read_b128 v[214:217], v149 offset:4096
	ds_read_b128 v[218:221], v149 offset:5120
	ds_read_b128 v[222:225], v149 offset:6144
	ds_read_b128 v[226:229], v149 offset:7168
	global_load_lds_dwordx4 v[144:145], off
	v_lshl_add_u64 v[144:145], s[6:7], 0, v[138:139]
	s_add_i32 m0, s3, 0xe000
	s_nop 0
	global_load_lds_dwordx4 v[144:145], off
	s_waitcnt vmcnt(8)
	s_waitcnt lgkmcnt(0)
	s_barrier
	s_setprio 1
	s_waitcnt lgkmcnt(0)
	v_mfma_f32_16x16x32_bf16 v[126:129], v[140:143], v[178:181], v[126:129]
	v_mfma_f32_16x16x32_bf16 v[118:121], v[154:157], v[178:181], v[118:121]
	v_mfma_f32_16x16x32_bf16 v[110:113], v[140:143], v[190:193], v[110:113]
	v_mfma_f32_16x16x32_bf16 v[102:105], v[154:157], v[190:193], v[102:105]
	v_mfma_f32_16x16x32_bf16 v[94:97], v[140:143], v[214:217], v[94:97]
	v_mfma_f32_16x16x32_bf16 v[86:89], v[154:157], v[214:217], v[86:89]
	v_mfma_f32_16x16x32_bf16 v[78:81], v[140:143], v[222:225], v[78:81]
	v_mfma_f32_16x16x32_bf16 v[70:73], v[154:157], v[222:225], v[70:73]
	v_mfma_f32_16x16x32_bf16 v[126:129], v[150:153], v[186:189], v[126:129]
	v_mfma_f32_16x16x32_bf16 v[118:121], v[158:161], v[186:189], v[118:121]
	v_mfma_f32_16x16x32_bf16 v[110:113], v[150:153], v[194:197], v[110:113]
	v_mfma_f32_16x16x32_bf16 v[102:105], v[158:161], v[194:197], v[102:105]
	v_mfma_f32_16x16x32_bf16 v[94:97], v[150:153], v[218:221], v[94:97]
	v_mfma_f32_16x16x32_bf16 v[86:89], v[158:161], v[218:221], v[86:89]
	v_mfma_f32_16x16x32_bf16 v[78:81], v[150:153], v[226:229], v[78:81]
	v_mfma_f32_16x16x32_bf16 v[70:73], v[158:161], v[226:229], v[70:73]
	v_mfma_f32_16x16x32_bf16 v[122:125], v[162:165], v[178:181], v[122:125]
	v_mfma_f32_16x16x32_bf16 v[114:117], v[170:173], v[178:181], v[114:117]
	v_mfma_f32_16x16x32_bf16 v[106:109], v[162:165], v[190:193], v[106:109]
	v_mfma_f32_16x16x32_bf16 v[98:101], v[170:173], v[190:193], v[98:101]
	v_mfma_f32_16x16x32_bf16 v[90:93], v[162:165], v[214:217], v[90:93]
	v_mfma_f32_16x16x32_bf16 v[82:85], v[170:173], v[214:217], v[82:85]
	v_mfma_f32_16x16x32_bf16 v[74:77], v[162:165], v[222:225], v[74:77]
	v_mfma_f32_16x16x32_bf16 v[66:69], v[170:173], v[222:225], v[66:69]
	v_mfma_f32_16x16x32_bf16 v[122:125], v[166:169], v[186:189], v[122:125]
	v_mfma_f32_16x16x32_bf16 v[114:117], v[174:177], v[186:189], v[114:117]
	v_mfma_f32_16x16x32_bf16 v[106:109], v[166:169], v[194:197], v[106:109]
	v_mfma_f32_16x16x32_bf16 v[98:101], v[174:177], v[194:197], v[98:101]
	v_mfma_f32_16x16x32_bf16 v[90:93], v[166:169], v[218:221], v[90:93]
	v_mfma_f32_16x16x32_bf16 v[82:85], v[174:177], v[218:221], v[82:85]
	v_mfma_f32_16x16x32_bf16 v[74:77], v[166:169], v[226:229], v[74:77]
	v_mfma_f32_16x16x32_bf16 v[66:69], v[174:177], v[226:229], v[66:69]
	s_setprio 0
	s_barrier
	s_add_i32 s18, s18, s28
	v_lshl_add_u64 v[144:145], s[8:9], 0, v[0:1]
	s_mov_b32 m0, s18
	ds_read_b128 v[178:181], v149 offset:16384
	ds_read_b128 v[186:189], v149 offset:17408
	ds_read_b128 v[190:193], v149 offset:18432
	ds_read_b128 v[194:197], v149 offset:19456
	ds_read_b128 v[214:217], v149 offset:20480
	ds_read_b128 v[218:221], v149 offset:21504
	ds_read_b128 v[222:225], v149 offset:22528
	ds_read_b128 v[226:229], v149 offset:23552
	global_load_lds_dwordx4 v[144:145], off
	s_add_i32 m0, s18, 0x2000
	s_add_u32 s56, s8, 0x40000
	v_lshl_add_u64 v[182:183], s[8:9], 0, v[130:131]
	s_addc_u32 s57, s9, 0
	s_add_i32 s18, s19, s28
	global_load_lds_dwordx4 v[182:183], off
	v_lshl_add_u64 v[184:185], s[56:57], 0, v[0:1]
	s_mov_b32 m0, s18
	v_lshl_add_u64 v[210:211], s[10:11], 0, v[132:133]
	global_load_lds_dwordx4 v[184:185], off
	v_lshl_add_u64 v[184:185], s[56:57], 0, v[130:131]
	s_add_i32 m0, s18, 0x2000
	s_nop 0
	global_load_lds_dwordx4 v[184:185], off
	v_lshl_add_u64 v[184:185], s[10:11], 0, v[134:135]
	s_mov_b32 m0, s3
	s_nop 0
	global_load_lds_dwordx4 v[184:185], off
	s_mov_b32 m0, s5
	s_nop 0
	global_load_lds_dwordx4 v[210:211], off
	s_waitcnt vmcnt(8)
	s_waitcnt lgkmcnt(0)
	s_barrier
	s_setprio 1
	s_waitcnt lgkmcnt(0)
	v_mfma_f32_16x16x32_bf16 v[62:65], v[140:143], v[178:181], v[62:65]
	v_mfma_f32_16x16x32_bf16 v[54:57], v[154:157], v[178:181], v[54:57]
	v_mfma_f32_16x16x32_bf16 v[46:49], v[140:143], v[190:193], v[46:49]
	v_mfma_f32_16x16x32_bf16 v[38:41], v[154:157], v[190:193], v[38:41]
	v_mfma_f32_16x16x32_bf16 v[30:33], v[140:143], v[214:217], v[30:33]
	v_mfma_f32_16x16x32_bf16 v[22:25], v[154:157], v[214:217], v[22:25]
	v_mfma_f32_16x16x32_bf16 v[14:17], v[140:143], v[222:225], v[14:17]
	v_mfma_f32_16x16x32_bf16 v[6:9], v[154:157], v[222:225], v[6:9]
	v_mfma_f32_16x16x32_bf16 v[62:65], v[150:153], v[186:189], v[62:65]
	v_mfma_f32_16x16x32_bf16 v[54:57], v[158:161], v[186:189], v[54:57]
	v_mfma_f32_16x16x32_bf16 v[46:49], v[150:153], v[194:197], v[46:49]
	v_mfma_f32_16x16x32_bf16 v[38:41], v[158:161], v[194:197], v[38:41]
	v_mfma_f32_16x16x32_bf16 v[30:33], v[150:153], v[218:221], v[30:33]
	v_mfma_f32_16x16x32_bf16 v[22:25], v[158:161], v[218:221], v[22:25]
	v_mfma_f32_16x16x32_bf16 v[14:17], v[150:153], v[226:229], v[14:17]
	v_mfma_f32_16x16x32_bf16 v[6:9], v[158:161], v[226:229], v[6:9]
	v_mfma_f32_16x16x32_bf16 v[58:61], v[162:165], v[178:181], v[58:61]
	v_mfma_f32_16x16x32_bf16 v[50:53], v[170:173], v[178:181], v[50:53]
	v_mfma_f32_16x16x32_bf16 v[42:45], v[162:165], v[190:193], v[42:45]
	v_mfma_f32_16x16x32_bf16 v[34:37], v[170:173], v[190:193], v[34:37]
	v_mfma_f32_16x16x32_bf16 v[26:29], v[162:165], v[214:217], v[26:29]
	v_mfma_f32_16x16x32_bf16 v[18:21], v[170:173], v[214:217], v[18:21]
	v_mfma_f32_16x16x32_bf16 v[10:13], v[162:165], v[222:225], v[10:13]
	v_mfma_f32_16x16x32_bf16 v[2:5], v[170:173], v[222:225], v[2:5]
	v_mfma_f32_16x16x32_bf16 v[58:61], v[166:169], v[186:189], v[58:61]
	v_mfma_f32_16x16x32_bf16 v[50:53], v[174:177], v[186:189], v[50:53]
	v_mfma_f32_16x16x32_bf16 v[42:45], v[166:169], v[194:197], v[42:45]
	v_mfma_f32_16x16x32_bf16 v[34:37], v[174:177], v[194:197], v[34:37]
	v_mfma_f32_16x16x32_bf16 v[26:29], v[166:169], v[218:221], v[26:29]
	v_mfma_f32_16x16x32_bf16 v[18:21], v[174:177], v[218:221], v[18:21]
	v_mfma_f32_16x16x32_bf16 v[10:13], v[166:169], v[226:229], v[10:13]
	v_mfma_f32_16x16x32_bf16 v[2:5], v[174:177], v[226:229], v[2:5]
	s_setprio 0
	s_barrier
	s_add_i32 s18, 0, 0x18000
	s_add_i32 s19, 0, 0x1c000
	v_add_u32_e32 v158, s18, v147
	v_add_u32_e32 v174, s19, v147
	ds_read_b128 v[140:143], v158
	ds_read_b128 v[150:153], v158 offset:1024
	ds_read_b128 v[154:157], v158 offset:2048
	ds_read_b128 v[158:161], v158 offset:3072
	ds_read_b128 v[162:165], v174
	ds_read_b128 v[166:169], v174 offset:1024
	ds_read_b128 v[170:173], v174 offset:2048
	ds_read_b128 v[174:177], v174 offset:3072
	s_add_u32 s10, s10, 0x40000
	s_addc_u32 s11, s11, 0
	s_mov_b32 m0, s29
	v_lshl_add_u64 v[230:231], s[10:11], 0, v[134:135]
	ds_read_b128 v[178:181], v149 offset:32768
	ds_read_b128 v[186:189], v149 offset:33792
	ds_read_b128 v[190:193], v149 offset:34816
	ds_read_b128 v[194:197], v149 offset:35840
	ds_read_b128 v[214:217], v149 offset:36864
	ds_read_b128 v[218:221], v149 offset:37888
	ds_read_b128 v[222:225], v149 offset:38912
	ds_read_b128 v[226:229], v149 offset:39936
	global_load_lds_dwordx4 v[230:231], off
	v_lshl_add_u64 v[230:231], s[10:11], 0, v[132:133]
	s_mov_b32 m0, s30
	s_nop 0
	global_load_lds_dwordx4 v[230:231], off
	s_waitcnt vmcnt(8)
	s_waitcnt lgkmcnt(0)
	s_barrier
	s_setprio 1
	s_waitcnt lgkmcnt(0)
	v_mfma_f32_16x16x32_bf16 v[126:129], v[140:143], v[178:181], v[126:129]
	v_mfma_f32_16x16x32_bf16 v[118:121], v[154:157], v[178:181], v[118:121]
	v_mfma_f32_16x16x32_bf16 v[110:113], v[140:143], v[190:193], v[110:113]
	v_mfma_f32_16x16x32_bf16 v[102:105], v[154:157], v[190:193], v[102:105]
	v_mfma_f32_16x16x32_bf16 v[94:97], v[140:143], v[214:217], v[94:97]
	v_mfma_f32_16x16x32_bf16 v[86:89], v[154:157], v[214:217], v[86:89]
	v_mfma_f32_16x16x32_bf16 v[78:81], v[140:143], v[222:225], v[78:81]
	v_mfma_f32_16x16x32_bf16 v[70:73], v[154:157], v[222:225], v[70:73]
	v_mfma_f32_16x16x32_bf16 v[126:129], v[150:153], v[186:189], v[126:129]
	v_mfma_f32_16x16x32_bf16 v[118:121], v[158:161], v[186:189], v[118:121]
	v_mfma_f32_16x16x32_bf16 v[110:113], v[150:153], v[194:197], v[110:113]
	v_mfma_f32_16x16x32_bf16 v[102:105], v[158:161], v[194:197], v[102:105]
	v_mfma_f32_16x16x32_bf16 v[94:97], v[150:153], v[218:221], v[94:97]
	v_mfma_f32_16x16x32_bf16 v[86:89], v[158:161], v[218:221], v[86:89]
	v_mfma_f32_16x16x32_bf16 v[78:81], v[150:153], v[226:229], v[78:81]
	v_mfma_f32_16x16x32_bf16 v[70:73], v[158:161], v[226:229], v[70:73]
	v_mfma_f32_16x16x32_bf16 v[122:125], v[162:165], v[178:181], v[122:125]
	v_mfma_f32_16x16x32_bf16 v[114:117], v[170:173], v[178:181], v[114:117]
	v_mfma_f32_16x16x32_bf16 v[106:109], v[162:165], v[190:193], v[106:109]
	v_mfma_f32_16x16x32_bf16 v[98:101], v[170:173], v[190:193], v[98:101]
	v_mfma_f32_16x16x32_bf16 v[90:93], v[162:165], v[214:217], v[90:93]
	v_mfma_f32_16x16x32_bf16 v[82:85], v[170:173], v[214:217], v[82:85]
	v_mfma_f32_16x16x32_bf16 v[74:77], v[162:165], v[222:225], v[74:77]
	v_mfma_f32_16x16x32_bf16 v[66:69], v[170:173], v[222:225], v[66:69]
	v_mfma_f32_16x16x32_bf16 v[122:125], v[166:169], v[186:189], v[122:125]
	v_mfma_f32_16x16x32_bf16 v[114:117], v[174:177], v[186:189], v[114:117]
	v_mfma_f32_16x16x32_bf16 v[106:109], v[166:169], v[194:197], v[106:109]
	v_mfma_f32_16x16x32_bf16 v[98:101], v[174:177], v[194:197], v[98:101]
	v_mfma_f32_16x16x32_bf16 v[90:93], v[166:169], v[218:221], v[90:93]
	v_mfma_f32_16x16x32_bf16 v[82:85], v[174:177], v[218:221], v[82:85]
	v_mfma_f32_16x16x32_bf16 v[74:77], v[166:169], v[226:229], v[74:77]
	v_mfma_f32_16x16x32_bf16 v[66:69], v[174:177], v[226:229], v[66:69]
	s_setprio 0
	s_barrier
	s_add_i32 s10, s18, s28
	v_lshl_add_u64 v[144:145], v[144:145], 0, s[54:55]
	s_mov_b32 m0, s10
	ds_read_b128 v[178:181], v149 offset:49152
	ds_read_b128 v[186:189], v149 offset:50176
	ds_read_b128 v[190:193], v149 offset:51200
	ds_read_b128 v[194:197], v149 offset:52224
	ds_read_b128 v[214:217], v149 offset:53248
	ds_read_b128 v[218:221], v149 offset:54272
	ds_read_b128 v[222:225], v149 offset:55296
	ds_read_b128 v[226:229], v149 offset:56320
	global_load_lds_dwordx4 v[144:145], off
	s_add_i32 m0, s10, 0x2000
	s_add_u32 s8, s8, 0x40080
	v_lshl_add_u64 v[144:145], v[182:183], 0, s[54:55]
	s_addc_u32 s9, s9, 0
	s_add_i32 s10, s19, s28
	global_load_lds_dwordx4 v[144:145], off
	v_lshl_add_u64 v[144:145], s[8:9], 0, v[0:1]
	s_mov_b32 m0, s10
	s_nop 0
	global_load_lds_dwordx4 v[144:145], off
	v_lshl_add_u64 v[144:145], s[8:9], 0, v[130:131]
	s_add_i32 m0, s10, 0x2000
	s_nop 0
	global_load_lds_dwordx4 v[144:145], off
	v_lshl_add_u64 v[144:145], v[184:185], 0, s[54:55]
	s_mov_b32 m0, s31
	s_nop 0
	global_load_lds_dwordx4 v[144:145], off
	v_lshl_add_u64 v[144:145], v[210:211], 0, s[54:55]
	s_mov_b32 m0, s34
	s_nop 0
	global_load_lds_dwordx4 v[144:145], off
	s_waitcnt vmcnt(8)
	s_waitcnt lgkmcnt(0)
	s_barrier
	s_setprio 1
	s_waitcnt lgkmcnt(0)
	v_mfma_f32_16x16x32_bf16 v[62:65], v[140:143], v[178:181], v[62:65]
	v_mfma_f32_16x16x32_bf16 v[54:57], v[154:157], v[178:181], v[54:57]
	v_mfma_f32_16x16x32_bf16 v[46:49], v[140:143], v[190:193], v[46:49]
	v_mfma_f32_16x16x32_bf16 v[38:41], v[154:157], v[190:193], v[38:41]
	v_mfma_f32_16x16x32_bf16 v[30:33], v[140:143], v[214:217], v[30:33]
	v_mfma_f32_16x16x32_bf16 v[22:25], v[154:157], v[214:217], v[22:25]
	v_mfma_f32_16x16x32_bf16 v[14:17], v[140:143], v[222:225], v[14:17]
	v_mfma_f32_16x16x32_bf16 v[6:9], v[154:157], v[222:225], v[6:9]
	v_mfma_f32_16x16x32_bf16 v[62:65], v[150:153], v[186:189], v[62:65]
	v_mfma_f32_16x16x32_bf16 v[54:57], v[158:161], v[186:189], v[54:57]
	v_mfma_f32_16x16x32_bf16 v[46:49], v[150:153], v[194:197], v[46:49]
	v_mfma_f32_16x16x32_bf16 v[38:41], v[158:161], v[194:197], v[38:41]
	v_mfma_f32_16x16x32_bf16 v[30:33], v[150:153], v[218:221], v[30:33]
	v_mfma_f32_16x16x32_bf16 v[22:25], v[158:161], v[218:221], v[22:25]
	v_mfma_f32_16x16x32_bf16 v[14:17], v[150:153], v[226:229], v[14:17]
	v_mfma_f32_16x16x32_bf16 v[6:9], v[158:161], v[226:229], v[6:9]
	v_mfma_f32_16x16x32_bf16 v[58:61], v[162:165], v[178:181], v[58:61]
	v_mfma_f32_16x16x32_bf16 v[50:53], v[170:173], v[178:181], v[50:53]
	v_mfma_f32_16x16x32_bf16 v[42:45], v[162:165], v[190:193], v[42:45]
	v_mfma_f32_16x16x32_bf16 v[34:37], v[170:173], v[190:193], v[34:37]
	v_mfma_f32_16x16x32_bf16 v[26:29], v[162:165], v[214:217], v[26:29]
	v_mfma_f32_16x16x32_bf16 v[18:21], v[170:173], v[214:217], v[18:21]
	v_mfma_f32_16x16x32_bf16 v[10:13], v[162:165], v[222:225], v[10:13]
	v_mfma_f32_16x16x32_bf16 v[2:5], v[170:173], v[222:225], v[2:5]
	v_mfma_f32_16x16x32_bf16 v[58:61], v[166:169], v[186:189], v[58:61]
	v_mfma_f32_16x16x32_bf16 v[50:53], v[174:177], v[186:189], v[50:53]
	v_mfma_f32_16x16x32_bf16 v[42:45], v[166:169], v[194:197], v[42:45]
	v_mfma_f32_16x16x32_bf16 v[34:37], v[174:177], v[194:197], v[34:37]
	v_mfma_f32_16x16x32_bf16 v[26:29], v[166:169], v[218:221], v[26:29]
	v_mfma_f32_16x16x32_bf16 v[18:21], v[174:177], v[218:221], v[18:21]
	v_mfma_f32_16x16x32_bf16 v[10:13], v[166:169], v[226:229], v[10:13]
	v_mfma_f32_16x16x32_bf16 v[2:5], v[174:177], v[226:229], v[2:5]
	s_setprio 0
	s_barrier
	s_add_i32 s49, s49, 2
	s_add_u32 s6, s6, 0x100
	s_addc_u32 s7, s7, 0
	s_add_u32 s36, s36, 0x100
	s_addc_u32 s37, s37, 0
	s_cmp_gt_u32 s49, 13
	s_cbranch_scc0 .LBB0_1171
	s_and_b64 vcc, exec, s[46:47]
	s_cbranch_vccz .LBB0_1174
	s_barrier

.LBB0_1247:
	s_add_u32 s8, s2, 0x100
	s_addc_u32 s9, s3, 0
	s_add_i32 s18, 0, 0x10000
	s_cmp_eq_u32 s40, 40
	s_cselect_b32 s17, s5, s9
	s_cselect_b32 s16, s4, s8
	v_add_u32_e32 v159, s18, v156
	s_cselect_b32 s11, s7, s1
	s_cselect_b32 s10, s6, s0
	s_add_i32 s19, 0, 0x14000
	ds_read_b128 v[152:155], v159
	ds_read_b128 v[160:163], v159 offset:1024
	ds_read_b128 v[164:167], v159 offset:2048
	ds_read_b128 v[168:171], v159 offset:3072
	v_add_u32_e32 v159, s19, v156
	ds_read_b128 v[172:175], v159
	ds_read_b128 v[176:179], v159 offset:1024
	ds_read_b128 v[186:189], v159 offset:2048
	ds_read_b128 v[190:193], v159 offset:3072
	v_lshl_add_u64 v[180:181], s[2:3], 0, v[148:149]
	s_add_i32 m0, s23, 0xc000
	ds_read_b128 v[194:197], v158
	ds_read_b128 v[214:217], v158 offset:1024
	ds_read_b128 v[218:221], v158 offset:2048
	ds_read_b128 v[222:225], v158 offset:3072
	ds_read_b128 v[226:229], v158 offset:4096
	ds_read_b128 v[230:233], v158 offset:5120
	ds_read_b128 v[240:243], v158 offset:6144
	ds_read_b128 v[244:247], v158 offset:7168
	global_load_lds_dwordx4 v[180:181], off
	v_lshl_add_u64 v[180:181], s[2:3], 0, v[150:151]
	s_add_i32 m0, s23, 0xe000
	s_nop 0
	global_load_lds_dwordx4 v[180:181], off
	s_waitcnt vmcnt(8)
	s_waitcnt lgkmcnt(0)
	s_barrier
	s_setprio 1
	s_waitcnt lgkmcnt(0)
	v_mfma_f32_16x16x32_bf16 v[126:129], v[152:155], v[194:197], v[126:129]
	v_mfma_f32_16x16x32_bf16 v[98:101], v[164:167], v[194:197], v[98:101]
	v_mfma_f32_16x16x32_bf16 v[122:125], v[152:155], v[218:221], v[122:125]
	v_mfma_f32_16x16x32_bf16 v[90:93], v[164:167], v[218:221], v[90:93]
	v_mfma_f32_16x16x32_bf16 v[118:121], v[152:155], v[226:229], v[118:121]
	v_mfma_f32_16x16x32_bf16 v[86:89], v[164:167], v[226:229], v[86:89]
	v_mfma_f32_16x16x32_bf16 v[114:117], v[152:155], v[240:243], v[114:117]
	v_mfma_f32_16x16x32_bf16 v[82:85], v[164:167], v[240:243], v[82:85]
	v_mfma_f32_16x16x32_bf16 v[126:129], v[160:163], v[214:217], v[126:129]
	v_mfma_f32_16x16x32_bf16 v[98:101], v[168:171], v[214:217], v[98:101]
	v_mfma_f32_16x16x32_bf16 v[122:125], v[160:163], v[222:225], v[122:125]
	v_mfma_f32_16x16x32_bf16 v[90:93], v[168:171], v[222:225], v[90:93]
	v_mfma_f32_16x16x32_bf16 v[118:121], v[160:163], v[230:233], v[118:121]
	v_mfma_f32_16x16x32_bf16 v[86:89], v[168:171], v[230:233], v[86:89]
	v_mfma_f32_16x16x32_bf16 v[114:117], v[160:163], v[244:247], v[114:117]
	v_mfma_f32_16x16x32_bf16 v[82:85], v[168:171], v[244:247], v[82:85]
	v_mfma_f32_16x16x32_bf16 v[66:69], v[172:175], v[194:197], v[66:69]
	v_mfma_f32_16x16x32_bf16 v[34:37], v[186:189], v[194:197], v[34:37]
	v_mfma_f32_16x16x32_bf16 v[58:61], v[172:175], v[218:221], v[58:61]
	v_mfma_f32_16x16x32_bf16 v[26:29], v[186:189], v[218:221], v[26:29]
	v_mfma_f32_16x16x32_bf16 v[54:57], v[172:175], v[226:229], v[54:57]
	v_mfma_f32_16x16x32_bf16 v[22:25], v[186:189], v[226:229], v[22:25]
	v_mfma_f32_16x16x32_bf16 v[50:53], v[172:175], v[240:243], v[50:53]
	v_mfma_f32_16x16x32_bf16 v[18:21], v[186:189], v[240:243], v[18:21]
	v_mfma_f32_16x16x32_bf16 v[66:69], v[176:179], v[214:217], v[66:69]
	v_mfma_f32_16x16x32_bf16 v[34:37], v[190:193], v[214:217], v[34:37]
	v_mfma_f32_16x16x32_bf16 v[58:61], v[176:179], v[222:225], v[58:61]
	v_mfma_f32_16x16x32_bf16 v[26:29], v[190:193], v[222:225], v[26:29]
	v_mfma_f32_16x16x32_bf16 v[54:57], v[176:179], v[230:233], v[54:57]
	v_mfma_f32_16x16x32_bf16 v[22:25], v[190:193], v[230:233], v[22:25]
	v_mfma_f32_16x16x32_bf16 v[50:53], v[176:179], v[244:247], v[50:53]
	v_mfma_f32_16x16x32_bf16 v[18:21], v[190:193], v[244:247], v[18:21]
	s_setprio 0
	s_barrier
	s_add_i32 s2, s18, s22
	v_lshl_add_u64 v[180:181], s[10:11], 0, v[0:1]
	s_mov_b32 m0, s2
	ds_read_b128 v[194:197], v158 offset:16384
	ds_read_b128 v[214:217], v158 offset:17408
	ds_read_b128 v[218:221], v158 offset:18432
	ds_read_b128 v[222:225], v158 offset:19456
	ds_read_b128 v[226:229], v158 offset:20480
	ds_read_b128 v[230:233], v158 offset:21504
	ds_read_b128 v[240:243], v158 offset:22528
	ds_read_b128 v[244:247], v158 offset:23552
	global_load_lds_dwordx4 v[180:181], off
	s_add_i32 m0, s2, 0x2000
	s_add_u32 s2, s10, 0xb0000
	v_lshl_add_u64 v[182:183], s[10:11], 0, v[130:131]
	s_addc_u32 s3, s11, 0
	s_add_i32 s18, s19, s22
	global_load_lds_dwordx4 v[182:183], off
	v_lshl_add_u64 v[184:185], s[2:3], 0, v[0:1]
	s_mov_b32 m0, s18
	v_lshl_add_u64 v[210:211], s[16:17], 0, v[130:131]
	global_load_lds_dwordx4 v[184:185], off
	v_lshl_add_u64 v[184:185], s[2:3], 0, v[130:131]
	s_add_i32 m0, s18, 0x2000
	s_nop 0
	global_load_lds_dwordx4 v[184:185], off
	v_lshl_add_u64 v[184:185], s[16:17], 0, v[0:1]
	s_mov_b32 m0, s23
	s_nop 0
	global_load_lds_dwordx4 v[184:185], off
	s_mov_b32 m0, s24
	s_nop 0
	global_load_lds_dwordx4 v[210:211], off
	s_waitcnt vmcnt(8)
	s_waitcnt lgkmcnt(0)
	s_barrier
	s_setprio 1
	s_waitcnt lgkmcnt(0)
	v_mfma_f32_16x16x32_bf16 v[110:113], v[152:155], v[194:197], v[110:113]
	v_mfma_f32_16x16x32_bf16 v[78:81], v[164:167], v[194:197], v[78:81]
	v_mfma_f32_16x16x32_bf16 v[106:109], v[152:155], v[218:221], v[106:109]
	v_mfma_f32_16x16x32_bf16 v[74:77], v[164:167], v[218:221], v[74:77]
	v_mfma_f32_16x16x32_bf16 v[102:105], v[152:155], v[226:229], v[102:105]
	v_mfma_f32_16x16x32_bf16 v[70:73], v[164:167], v[226:229], v[70:73]
	v_mfma_f32_16x16x32_bf16 v[94:97], v[152:155], v[240:243], v[94:97]
	v_mfma_f32_16x16x32_bf16 v[62:65], v[164:167], v[240:243], v[62:65]
	v_mfma_f32_16x16x32_bf16 v[110:113], v[160:163], v[214:217], v[110:113]
	v_mfma_f32_16x16x32_bf16 v[78:81], v[168:171], v[214:217], v[78:81]
	v_mfma_f32_16x16x32_bf16 v[106:109], v[160:163], v[222:225], v[106:109]
	v_mfma_f32_16x16x32_bf16 v[74:77], v[168:171], v[222:225], v[74:77]
	v_mfma_f32_16x16x32_bf16 v[102:105], v[160:163], v[230:233], v[102:105]
	v_mfma_f32_16x16x32_bf16 v[70:73], v[168:171], v[230:233], v[70:73]
	v_mfma_f32_16x16x32_bf16 v[94:97], v[160:163], v[244:247], v[94:97]
	v_mfma_f32_16x16x32_bf16 v[62:65], v[168:171], v[244:247], v[62:65]
	v_mfma_f32_16x16x32_bf16 v[46:49], v[172:175], v[194:197], v[46:49]
	v_mfma_f32_16x16x32_bf16 v[14:17], v[186:189], v[194:197], v[14:17]
	v_mfma_f32_16x16x32_bf16 v[42:45], v[172:175], v[218:221], v[42:45]
	v_mfma_f32_16x16x32_bf16 v[10:13], v[186:189], v[218:221], v[10:13]
	v_mfma_f32_16x16x32_bf16 v[38:41], v[172:175], v[226:229], v[38:41]
	v_mfma_f32_16x16x32_bf16 v[6:9], v[186:189], v[226:229], v[6:9]
	v_mfma_f32_16x16x32_bf16 v[30:33], v[172:175], v[240:243], v[30:33]
	v_mfma_f32_16x16x32_bf16 v[2:5], v[186:189], v[240:243], v[2:5]
	v_mfma_f32_16x16x32_bf16 v[46:49], v[176:179], v[214:217], v[46:49]
	v_mfma_f32_16x16x32_bf16 v[14:17], v[190:193], v[214:217], v[14:17]
	v_mfma_f32_16x16x32_bf16 v[42:45], v[176:179], v[222:225], v[42:45]
	v_mfma_f32_16x16x32_bf16 v[10:13], v[190:193], v[222:225], v[10:13]
	v_mfma_f32_16x16x32_bf16 v[38:41], v[176:179], v[230:233], v[38:41]
	v_mfma_f32_16x16x32_bf16 v[6:9], v[190:193], v[230:233], v[6:9]
	v_mfma_f32_16x16x32_bf16 v[30:33], v[176:179], v[244:247], v[30:33]
	v_mfma_f32_16x16x32_bf16 v[2:5], v[190:193], v[244:247], v[2:5]
	s_setprio 0
	s_barrier
	s_add_i32 s18, 0, 0x18000
	v_add_u32_e32 v159, s18, v156
	s_add_i32 s19, 0, 0x1c000
	ds_read_b128 v[152:155], v159
	ds_read_b128 v[160:163], v159 offset:1024
	ds_read_b128 v[164:167], v159 offset:2048
	ds_read_b128 v[168:171], v159 offset:3072
	v_add_u32_e32 v159, s19, v156
	ds_read_b128 v[172:175], v159
	ds_read_b128 v[176:179], v159 offset:1024
	ds_read_b128 v[186:189], v159 offset:2048
	ds_read_b128 v[190:193], v159 offset:3072
	s_add_u32 s2, s16, 0xb0000
	s_addc_u32 s3, s17, 0
	s_mov_b32 m0, s25
	v_lshl_add_u64 v[234:235], s[2:3], 0, v[0:1]
	ds_read_b128 v[194:197], v158 offset:32768
	ds_read_b128 v[214:217], v158 offset:33792
	ds_read_b128 v[218:221], v158 offset:34816
	ds_read_b128 v[222:225], v158 offset:35840
	ds_read_b128 v[226:229], v158 offset:36864
	ds_read_b128 v[230:233], v158 offset:37888
	ds_read_b128 v[240:243], v158 offset:38912
	ds_read_b128 v[244:247], v158 offset:39936
	global_load_lds_dwordx4 v[234:235], off
	v_lshl_add_u64 v[234:235], s[2:3], 0, v[130:131]
	s_mov_b32 m0, s28
	s_nop 0
	global_load_lds_dwordx4 v[234:235], off
	s_waitcnt vmcnt(8)
	s_waitcnt lgkmcnt(0)
	s_barrier
	s_setprio 1
	s_waitcnt lgkmcnt(0)
	v_mfma_f32_16x16x32_bf16 v[126:129], v[152:155], v[194:197], v[126:129]
	v_mfma_f32_16x16x32_bf16 v[98:101], v[164:167], v[194:197], v[98:101]
	v_mfma_f32_16x16x32_bf16 v[122:125], v[152:155], v[218:221], v[122:125]
	v_mfma_f32_16x16x32_bf16 v[90:93], v[164:167], v[218:221], v[90:93]
	v_mfma_f32_16x16x32_bf16 v[118:121], v[152:155], v[226:229], v[118:121]
	v_mfma_f32_16x16x32_bf16 v[86:89], v[164:167], v[226:229], v[86:89]
	v_mfma_f32_16x16x32_bf16 v[114:117], v[152:155], v[240:243], v[114:117]
	v_mfma_f32_16x16x32_bf16 v[82:85], v[164:167], v[240:243], v[82:85]
	v_mfma_f32_16x16x32_bf16 v[126:129], v[160:163], v[214:217], v[126:129]
	v_mfma_f32_16x16x32_bf16 v[98:101], v[168:171], v[214:217], v[98:101]
	v_mfma_f32_16x16x32_bf16 v[122:125], v[160:163], v[222:225], v[122:125]
	v_mfma_f32_16x16x32_bf16 v[90:93], v[168:171], v[222:225], v[90:93]
	v_mfma_f32_16x16x32_bf16 v[118:121], v[160:163], v[230:233], v[118:121]
	v_mfma_f32_16x16x32_bf16 v[86:89], v[168:171], v[230:233], v[86:89]
	v_mfma_f32_16x16x32_bf16 v[114:117], v[160:163], v[244:247], v[114:117]
	v_mfma_f32_16x16x32_bf16 v[82:85], v[168:171], v[244:247], v[82:85]
	v_mfma_f32_16x16x32_bf16 v[66:69], v[172:175], v[194:197], v[66:69]
	v_mfma_f32_16x16x32_bf16 v[34:37], v[186:189], v[194:197], v[34:37]
	v_mfma_f32_16x16x32_bf16 v[58:61], v[172:175], v[218:221], v[58:61]
	v_mfma_f32_16x16x32_bf16 v[26:29], v[186:189], v[218:221], v[26:29]
	v_mfma_f32_16x16x32_bf16 v[54:57], v[172:175], v[226:229], v[54:57]
	v_mfma_f32_16x16x32_bf16 v[22:25], v[186:189], v[226:229], v[22:25]
	v_mfma_f32_16x16x32_bf16 v[50:53], v[172:175], v[240:243], v[50:53]
	v_mfma_f32_16x16x32_bf16 v[18:21], v[186:189], v[240:243], v[18:21]
	v_mfma_f32_16x16x32_bf16 v[66:69], v[176:179], v[214:217], v[66:69]
	v_mfma_f32_16x16x32_bf16 v[34:37], v[190:193], v[214:217], v[34:37]
	v_mfma_f32_16x16x32_bf16 v[58:61], v[176:179], v[222:225], v[58:61]
	v_mfma_f32_16x16x32_bf16 v[26:29], v[190:193], v[222:225], v[26:29]
	v_mfma_f32_16x16x32_bf16 v[54:57], v[176:179], v[230:233], v[54:57]
	v_mfma_f32_16x16x32_bf16 v[22:25], v[190:193], v[230:233], v[22:25]
	v_mfma_f32_16x16x32_bf16 v[50:53], v[176:179], v[244:247], v[50:53]
	v_mfma_f32_16x16x32_bf16 v[18:21], v[190:193], v[244:247], v[18:21]
	s_setprio 0
	s_barrier
	s_add_i32 s2, s18, s22
	v_lshl_add_u64 v[180:181], v[180:181], 0, s[54:55]
	s_mov_b32 m0, s2
	ds_read_b128 v[194:197], v158 offset:49152
	ds_read_b128 v[214:217], v158 offset:50176
	ds_read_b128 v[218:221], v158 offset:51200
	ds_read_b128 v[222:225], v158 offset:52224
	ds_read_b128 v[226:229], v158 offset:53248
	ds_read_b128 v[230:233], v158 offset:54272
	ds_read_b128 v[240:243], v158 offset:55296
	ds_read_b128 v[244:247], v158 offset:56320
	global_load_lds_dwordx4 v[180:181], off
	s_add_i32 m0, s2, 0x2000
	s_add_u32 s2, s10, 0xb0080
	v_lshl_add_u64 v[180:181], v[182:183], 0, s[54:55]
	s_addc_u32 s3, s11, 0
	s_add_i32 s10, s19, s22
	global_load_lds_dwordx4 v[180:181], off
	v_lshl_add_u64 v[180:181], s[2:3], 0, v[0:1]
	s_mov_b32 m0, s10
	s_nop 0
	global_load_lds_dwordx4 v[180:181], off
	v_lshl_add_u64 v[180:181], s[2:3], 0, v[130:131]
	s_add_i32 m0, s10, 0x2000
	s_nop 0
	global_load_lds_dwordx4 v[180:181], off
	v_lshl_add_u64 v[180:181], v[184:185], 0, s[54:55]
	s_mov_b32 m0, s31
	s_nop 0
	global_load_lds_dwordx4 v[180:181], off
	v_lshl_add_u64 v[180:181], v[210:211], 0, s[54:55]
	s_mov_b32 m0, s34
	s_nop 0
	global_load_lds_dwordx4 v[180:181], off
	s_waitcnt vmcnt(8)
	s_waitcnt lgkmcnt(0)
	s_barrier
	s_setprio 1
	s_waitcnt lgkmcnt(0)
	v_mfma_f32_16x16x32_bf16 v[110:113], v[152:155], v[194:197], v[110:113]
	v_mfma_f32_16x16x32_bf16 v[78:81], v[164:167], v[194:197], v[78:81]
	v_mfma_f32_16x16x32_bf16 v[106:109], v[152:155], v[218:221], v[106:109]
	v_mfma_f32_16x16x32_bf16 v[74:77], v[164:167], v[218:221], v[74:77]
	v_mfma_f32_16x16x32_bf16 v[102:105], v[152:155], v[226:229], v[102:105]
	v_mfma_f32_16x16x32_bf16 v[70:73], v[164:167], v[226:229], v[70:73]
	v_mfma_f32_16x16x32_bf16 v[94:97], v[152:155], v[240:243], v[94:97]
	v_mfma_f32_16x16x32_bf16 v[62:65], v[164:167], v[240:243], v[62:65]
	v_mfma_f32_16x16x32_bf16 v[110:113], v[160:163], v[214:217], v[110:113]
	v_mfma_f32_16x16x32_bf16 v[78:81], v[168:171], v[214:217], v[78:81]
	v_mfma_f32_16x16x32_bf16 v[106:109], v[160:163], v[222:225], v[106:109]
	v_mfma_f32_16x16x32_bf16 v[74:77], v[168:171], v[222:225], v[74:77]
	v_mfma_f32_16x16x32_bf16 v[102:105], v[160:163], v[230:233], v[102:105]
	v_mfma_f32_16x16x32_bf16 v[70:73], v[168:171], v[230:233], v[70:73]
	v_mfma_f32_16x16x32_bf16 v[94:97], v[160:163], v[244:247], v[94:97]
	v_mfma_f32_16x16x32_bf16 v[62:65], v[168:171], v[244:247], v[62:65]
	v_mfma_f32_16x16x32_bf16 v[46:49], v[172:175], v[194:197], v[46:49]
	v_mfma_f32_16x16x32_bf16 v[14:17], v[186:189], v[194:197], v[14:17]
	v_mfma_f32_16x16x32_bf16 v[42:45], v[172:175], v[218:221], v[42:45]
	v_mfma_f32_16x16x32_bf16 v[10:13], v[186:189], v[218:221], v[10:13]
	v_mfma_f32_16x16x32_bf16 v[38:41], v[172:175], v[226:229], v[38:41]
	v_mfma_f32_16x16x32_bf16 v[6:9], v[186:189], v[226:229], v[6:9]
	v_mfma_f32_16x16x32_bf16 v[30:33], v[172:175], v[240:243], v[30:33]
	v_mfma_f32_16x16x32_bf16 v[2:5], v[186:189], v[240:243], v[2:5]
	v_mfma_f32_16x16x32_bf16 v[46:49], v[176:179], v[214:217], v[46:49]
	v_mfma_f32_16x16x32_bf16 v[14:17], v[190:193], v[214:217], v[14:17]
	v_mfma_f32_16x16x32_bf16 v[42:45], v[176:179], v[222:225], v[42:45]
	v_mfma_f32_16x16x32_bf16 v[10:13], v[190:193], v[222:225], v[10:13]
	v_mfma_f32_16x16x32_bf16 v[38:41], v[176:179], v[230:233], v[38:41]
	v_mfma_f32_16x16x32_bf16 v[6:9], v[190:193], v[230:233], v[6:9]
	v_mfma_f32_16x16x32_bf16 v[30:33], v[176:179], v[244:247], v[30:33]
	v_mfma_f32_16x16x32_bf16 v[2:5], v[190:193], v[244:247], v[2:5]
	s_setprio 0
	s_barrier
	s_add_i32 s40, s40, 2
	s_add_u32 s0, s0, 0x100
	s_addc_u32 s1, s1, 0
	s_cmp_gt_u32 s40, 41
	s_mov_b64 s[2:3], s[8:9]
	s_cbranch_scc0 .LBB0_1247
	s_and_b64 vcc, exec, s[46:47]
	s_cbranch_vccz .LBB0_1250
	s_barrier

.LBB0_1266:
	s_add_i32 s44, 0, 0x10000
	s_add_i32 s9, 0, 0x14000
	v_add_u32_e32 v224, s44, v134
	v_add_u32_e32 v225, s9, v134
	ds_read_b128 v[136:139], v224
	ds_read_b128 v[140:143], v224 offset:1024
	ds_read_b128 v[144:147], v224 offset:2048
	ds_read_b128 v[148:151], v224 offset:3072
	ds_read_b128 v[152:155], v225
	ds_read_b128 v[156:159], v225 offset:1024
	ds_read_b128 v[160:163], v225 offset:2048
	ds_read_b128 v[164:167], v225 offset:3072
	s_add_u32 s0, s10, 0xb0080
	s_addc_u32 s1, s11, 0
	s_add_i32 s47, s13, 0xc000
	v_lshl_add_u64 v[180:181], s[0:1], 0, v[0:1]
	s_mov_b32 m0, s47
	ds_read_b128 v[168:171], v135
	ds_read_b128 v[172:175], v135 offset:1024
	ds_read_b128 v[176:179], v135 offset:2048
	ds_read_b128 v[186:189], v135 offset:3072
	ds_read_b128 v[190:193], v135 offset:4096
	ds_read_b128 v[194:197], v135 offset:5120
	ds_read_b128 v[214:217], v135 offset:6144
	ds_read_b128 v[218:221], v135 offset:7168
	global_load_lds_dwordx4 v[180:181], off
	v_lshl_add_u64 v[180:181], s[0:1], 0, v[130:131]
	s_add_i32 s0, s13, 0xe000
	s_mov_b32 m0, s0
	s_nop 0
	global_load_lds_dwordx4 v[180:181], off
	s_waitcnt vmcnt(8)
	s_waitcnt lgkmcnt(0)
	s_barrier
	s_setprio 1
	s_waitcnt lgkmcnt(0)
	v_mfma_f32_16x16x32_bf16 v[126:129], v[136:139], v[168:171], v[126:129]
	v_mfma_f32_16x16x32_bf16 v[122:125], v[144:147], v[168:171], v[122:125]
	v_mfma_f32_16x16x32_bf16 v[118:121], v[136:139], v[176:179], v[118:121]
	v_mfma_f32_16x16x32_bf16 v[114:117], v[144:147], v[176:179], v[114:117]
	v_mfma_f32_16x16x32_bf16 v[110:113], v[136:139], v[190:193], v[110:113]
	v_mfma_f32_16x16x32_bf16 v[106:109], v[144:147], v[190:193], v[106:109]
	v_mfma_f32_16x16x32_bf16 v[86:89], v[136:139], v[214:217], v[86:89]
	v_mfma_f32_16x16x32_bf16 v[78:81], v[144:147], v[214:217], v[78:81]
	v_mfma_f32_16x16x32_bf16 v[126:129], v[140:143], v[172:175], v[126:129]
	v_mfma_f32_16x16x32_bf16 v[122:125], v[148:151], v[172:175], v[122:125]
	v_mfma_f32_16x16x32_bf16 v[118:121], v[140:143], v[186:189], v[118:121]
	v_mfma_f32_16x16x32_bf16 v[114:117], v[148:151], v[186:189], v[114:117]
	v_mfma_f32_16x16x32_bf16 v[110:113], v[140:143], v[194:197], v[110:113]
	v_mfma_f32_16x16x32_bf16 v[106:109], v[148:151], v[194:197], v[106:109]
	v_mfma_f32_16x16x32_bf16 v[86:89], v[140:143], v[218:221], v[86:89]
	v_mfma_f32_16x16x32_bf16 v[78:81], v[148:151], v[218:221], v[78:81]
	v_mfma_f32_16x16x32_bf16 v[102:105], v[152:155], v[168:171], v[102:105]
	v_mfma_f32_16x16x32_bf16 v[98:101], v[160:163], v[168:171], v[98:101]
	v_mfma_f32_16x16x32_bf16 v[94:97], v[152:155], v[176:179], v[94:97]
	v_mfma_f32_16x16x32_bf16 v[90:93], v[160:163], v[176:179], v[90:93]
	v_mfma_f32_16x16x32_bf16 v[82:85], v[152:155], v[190:193], v[82:85]
	v_mfma_f32_16x16x32_bf16 v[74:77], v[160:163], v[190:193], v[74:77]
	v_mfma_f32_16x16x32_bf16 v[70:73], v[152:155], v[214:217], v[70:73]
	v_mfma_f32_16x16x32_bf16 v[66:69], v[160:163], v[214:217], v[66:69]
	v_mfma_f32_16x16x32_bf16 v[102:105], v[156:159], v[172:175], v[102:105]
	v_mfma_f32_16x16x32_bf16 v[98:101], v[164:167], v[172:175], v[98:101]
	v_mfma_f32_16x16x32_bf16 v[94:97], v[156:159], v[186:189], v[94:97]
	v_mfma_f32_16x16x32_bf16 v[90:93], v[164:167], v[186:189], v[90:93]
	v_mfma_f32_16x16x32_bf16 v[82:85], v[156:159], v[194:197], v[82:85]
	v_mfma_f32_16x16x32_bf16 v[74:77], v[164:167], v[194:197], v[74:77]
	v_mfma_f32_16x16x32_bf16 v[70:73], v[156:159], v[218:221], v[70:73]
	v_mfma_f32_16x16x32_bf16 v[66:69], v[164:167], v[218:221], v[66:69]
	s_setprio 0
	s_barrier
	v_lshl_add_u64 v[180:181], s[2:3], 0, v[0:1]
	s_mov_b64 s[18:19], 0x100
	s_add_i32 s44, s44, s7
	v_lshl_add_u64 v[182:183], v[180:181], 0, s[18:19]
	s_mov_b32 m0, s44
	s_add_i32 s1, s44, 0x2000
	ds_read_b128 v[168:171], v135 offset:16384
	ds_read_b128 v[172:175], v135 offset:17408
	ds_read_b128 v[176:179], v135 offset:18432
	ds_read_b128 v[186:189], v135 offset:19456
	ds_read_b128 v[190:193], v135 offset:20480
	ds_read_b128 v[194:197], v135 offset:21504
	ds_read_b128 v[214:217], v135 offset:22528
	ds_read_b128 v[218:221], v135 offset:23552
	global_load_lds_dwordx4 v[182:183], off
	v_lshl_add_u64 v[182:183], s[2:3], 0, v[130:131]
	s_add_u32 s48, s2, 0xb0100
	v_lshl_add_u64 v[184:185], v[182:183], 0, s[18:19]
	s_mov_b32 m0, s1
	s_addc_u32 s49, s3, 0
	s_add_i32 s9, s9, s7
	global_load_lds_dwordx4 v[184:185], off
	v_lshl_add_u64 v[184:185], s[48:49], 0, v[0:1]
	s_mov_b32 m0, s9
	s_add_i32 s43, s9, 0x2000
	global_load_lds_dwordx4 v[184:185], off
	v_lshl_add_u64 v[184:185], s[48:49], 0, v[130:131]
	s_mov_b32 m0, s43
	s_nop 0
	global_load_lds_dwordx4 v[184:185], off
	v_lshl_add_u64 v[184:185], s[10:11], 0, v[0:1]
	v_lshl_add_u64 v[210:211], v[184:185], 0, s[18:19]
	s_mov_b32 m0, s13
	s_nop 0
	global_load_lds_dwordx4 v[210:211], off
	v_lshl_add_u64 v[210:211], s[10:11], 0, v[130:131]
	v_lshl_add_u64 v[222:223], v[210:211], 0, s[18:19]
	s_mov_b32 m0, s28
	s_nop 0
	global_load_lds_dwordx4 v[222:223], off
	s_waitcnt vmcnt(8)
	s_waitcnt lgkmcnt(0)
	s_barrier
	s_setprio 1
	s_waitcnt lgkmcnt(0)
	v_mfma_f32_16x16x32_bf16 v[62:65], v[136:139], v[168:171], v[62:65]
	v_mfma_f32_16x16x32_bf16 v[58:61], v[144:147], v[168:171], v[58:61]
	v_mfma_f32_16x16x32_bf16 v[54:57], v[136:139], v[176:179], v[54:57]
	v_mfma_f32_16x16x32_bf16 v[50:53], v[144:147], v[176:179], v[50:53]
	v_mfma_f32_16x16x32_bf16 v[38:41], v[136:139], v[190:193], v[38:41]
	v_mfma_f32_16x16x32_bf16 v[34:37], v[144:147], v[190:193], v[34:37]
	v_mfma_f32_16x16x32_bf16 v[22:25], v[136:139], v[214:217], v[22:25]
	v_mfma_f32_16x16x32_bf16 v[18:21], v[144:147], v[214:217], v[18:21]
	v_mfma_f32_16x16x32_bf16 v[62:65], v[140:143], v[172:175], v[62:65]
	v_mfma_f32_16x16x32_bf16 v[58:61], v[148:151], v[172:175], v[58:61]
	v_mfma_f32_16x16x32_bf16 v[54:57], v[140:143], v[186:189], v[54:57]
	v_mfma_f32_16x16x32_bf16 v[50:53], v[148:151], v[186:189], v[50:53]
	v_mfma_f32_16x16x32_bf16 v[38:41], v[140:143], v[194:197], v[38:41]
	v_mfma_f32_16x16x32_bf16 v[34:37], v[148:151], v[194:197], v[34:37]
	v_mfma_f32_16x16x32_bf16 v[22:25], v[140:143], v[218:221], v[22:25]
	v_mfma_f32_16x16x32_bf16 v[18:21], v[148:151], v[218:221], v[18:21]
	v_mfma_f32_16x16x32_bf16 v[46:49], v[152:155], v[168:171], v[46:49]
	v_mfma_f32_16x16x32_bf16 v[42:45], v[160:163], v[168:171], v[42:45]
	v_mfma_f32_16x16x32_bf16 v[30:33], v[152:155], v[176:179], v[30:33]
	v_mfma_f32_16x16x32_bf16 v[26:29], v[160:163], v[176:179], v[26:29]
	v_mfma_f32_16x16x32_bf16 v[14:17], v[152:155], v[190:193], v[14:17]
	v_mfma_f32_16x16x32_bf16 v[10:13], v[160:163], v[190:193], v[10:13]
	v_mfma_f32_16x16x32_bf16 v[6:9], v[152:155], v[214:217], v[6:9]
	v_mfma_f32_16x16x32_bf16 v[2:5], v[160:163], v[214:217], v[2:5]
	v_mfma_f32_16x16x32_bf16 v[46:49], v[156:159], v[172:175], v[46:49]
	v_mfma_f32_16x16x32_bf16 v[42:45], v[164:167], v[172:175], v[42:45]
	v_mfma_f32_16x16x32_bf16 v[30:33], v[156:159], v[186:189], v[30:33]
	v_mfma_f32_16x16x32_bf16 v[26:29], v[164:167], v[186:189], v[26:29]
	v_mfma_f32_16x16x32_bf16 v[14:17], v[156:159], v[194:197], v[14:17]
	v_mfma_f32_16x16x32_bf16 v[10:13], v[164:167], v[194:197], v[10:13]
	v_mfma_f32_16x16x32_bf16 v[6:9], v[156:159], v[218:221], v[6:9]
	v_mfma_f32_16x16x32_bf16 v[2:5], v[164:167], v[218:221], v[2:5]
	s_setprio 0
	s_barrier
	s_add_i32 s18, 0, 0x18000
	s_add_i32 s46, 0, 0x1c000
	v_add_u32_e32 v226, s18, v134
	v_add_u32_e32 v227, s46, v134
	ds_read_b128 v[136:139], v226
	ds_read_b128 v[140:143], v226 offset:1024
	ds_read_b128 v[144:147], v226 offset:2048
	ds_read_b128 v[148:151], v226 offset:3072
	ds_read_b128 v[152:155], v227
	ds_read_b128 v[156:159], v227 offset:1024
	ds_read_b128 v[160:163], v227 offset:2048
	ds_read_b128 v[164:167], v227 offset:3072
	s_add_u32 s48, s10, 0xb0100
	s_addc_u32 s49, s11, 0
	s_mov_b32 m0, s29
	v_lshl_add_u64 v[222:223], s[48:49], 0, v[0:1]
	ds_read_b128 v[168:171], v135 offset:32768
	ds_read_b128 v[172:175], v135 offset:33792
	ds_read_b128 v[176:179], v135 offset:34816
	ds_read_b128 v[186:189], v135 offset:35840
	ds_read_b128 v[190:193], v135 offset:36864
	ds_read_b128 v[194:197], v135 offset:37888
	ds_read_b128 v[214:217], v135 offset:38912
	ds_read_b128 v[218:221], v135 offset:39936
	global_load_lds_dwordx4 v[222:223], off
	v_lshl_add_u64 v[222:223], s[48:49], 0, v[130:131]
	s_mov_b32 m0, s30
	s_nop 0
	global_load_lds_dwordx4 v[222:223], off
	s_waitcnt vmcnt(8)
	s_waitcnt lgkmcnt(0)
	s_barrier
	s_setprio 1
	s_waitcnt lgkmcnt(0)
	v_mfma_f32_16x16x32_bf16 v[126:129], v[136:139], v[168:171], v[126:129]
	v_mfma_f32_16x16x32_bf16 v[122:125], v[144:147], v[168:171], v[122:125]
	v_mfma_f32_16x16x32_bf16 v[118:121], v[136:139], v[176:179], v[118:121]
	v_mfma_f32_16x16x32_bf16 v[114:117], v[144:147], v[176:179], v[114:117]
	v_mfma_f32_16x16x32_bf16 v[110:113], v[136:139], v[190:193], v[110:113]
	v_mfma_f32_16x16x32_bf16 v[106:109], v[144:147], v[190:193], v[106:109]
	v_mfma_f32_16x16x32_bf16 v[86:89], v[136:139], v[214:217], v[86:89]
	v_mfma_f32_16x16x32_bf16 v[78:81], v[144:147], v[214:217], v[78:81]
	v_mfma_f32_16x16x32_bf16 v[126:129], v[140:143], v[172:175], v[126:129]
	v_mfma_f32_16x16x32_bf16 v[122:125], v[148:151], v[172:175], v[122:125]
	v_mfma_f32_16x16x32_bf16 v[118:121], v[140:143], v[186:189], v[118:121]
	v_mfma_f32_16x16x32_bf16 v[114:117], v[148:151], v[186:189], v[114:117]
	v_mfma_f32_16x16x32_bf16 v[110:113], v[140:143], v[194:197], v[110:113]
	v_mfma_f32_16x16x32_bf16 v[106:109], v[148:151], v[194:197], v[106:109]
	v_mfma_f32_16x16x32_bf16 v[86:89], v[140:143], v[218:221], v[86:89]
	v_mfma_f32_16x16x32_bf16 v[78:81], v[148:151], v[218:221], v[78:81]
	v_mfma_f32_16x16x32_bf16 v[102:105], v[152:155], v[168:171], v[102:105]
	v_mfma_f32_16x16x32_bf16 v[98:101], v[160:163], v[168:171], v[98:101]
	v_mfma_f32_16x16x32_bf16 v[94:97], v[152:155], v[176:179], v[94:97]
	v_mfma_f32_16x16x32_bf16 v[90:93], v[160:163], v[176:179], v[90:93]
	v_mfma_f32_16x16x32_bf16 v[82:85], v[152:155], v[190:193], v[82:85]
	v_mfma_f32_16x16x32_bf16 v[74:77], v[160:163], v[190:193], v[74:77]
	v_mfma_f32_16x16x32_bf16 v[70:73], v[152:155], v[214:217], v[70:73]
	v_mfma_f32_16x16x32_bf16 v[66:69], v[160:163], v[214:217], v[66:69]
	v_mfma_f32_16x16x32_bf16 v[102:105], v[156:159], v[172:175], v[102:105]
	v_mfma_f32_16x16x32_bf16 v[98:101], v[164:167], v[172:175], v[98:101]
	v_mfma_f32_16x16x32_bf16 v[94:97], v[156:159], v[186:189], v[94:97]
	v_mfma_f32_16x16x32_bf16 v[90:93], v[164:167], v[186:189], v[90:93]
	v_mfma_f32_16x16x32_bf16 v[82:85], v[156:159], v[194:197], v[82:85]
	v_mfma_f32_16x16x32_bf16 v[74:77], v[164:167], v[194:197], v[74:77]
	v_mfma_f32_16x16x32_bf16 v[70:73], v[156:159], v[218:221], v[70:73]
	v_mfma_f32_16x16x32_bf16 v[66:69], v[164:167], v[218:221], v[66:69]
	s_setprio 0
	s_barrier
	s_add_i32 s49, s18, s7
	s_mov_b64 s[52:53], 0x180
	s_add_i32 s45, s49, 0x2000
	v_lshl_add_u64 v[180:181], v[180:181], 0, s[52:53]
	s_mov_b32 m0, s49
	s_add_u32 s50, s2, 0xb0180
	ds_read_b128 v[168:171], v135 offset:49152
	ds_read_b128 v[172:175], v135 offset:50176
	ds_read_b128 v[176:179], v135 offset:51200
	ds_read_b128 v[186:189], v135 offset:52224
	ds_read_b128 v[190:193], v135 offset:53248
	ds_read_b128 v[194:197], v135 offset:54272
	ds_read_b128 v[214:217], v135 offset:55296
	ds_read_b128 v[218:221], v135 offset:56320
	global_load_lds_dwordx4 v[180:181], off
	v_lshl_add_u64 v[180:181], v[182:183], 0, s[52:53]
	s_mov_b32 m0, s45
	s_addc_u32 s51, s3, 0
	s_add_i32 s46, s46, s7
	global_load_lds_dwordx4 v[180:181], off
	v_lshl_add_u64 v[180:181], s[50:51], 0, v[0:1]
	s_mov_b32 m0, s46
	s_add_i32 s48, s46, 0x2000
	global_load_lds_dwordx4 v[180:181], off
	v_lshl_add_u64 v[180:181], s[50:51], 0, v[130:131]
	s_mov_b32 m0, s48
	s_nop 0
	global_load_lds_dwordx4 v[180:181], off
	v_lshl_add_u64 v[180:181], v[184:185], 0, s[52:53]
	s_mov_b32 m0, s34
	s_nop 0
	global_load_lds_dwordx4 v[180:181], off
	v_lshl_add_u64 v[180:181], v[210:211], 0, s[52:53]
	s_mov_b32 m0, s35
	s_nop 0
	global_load_lds_dwordx4 v[180:181], off
	s_waitcnt vmcnt(8)
	s_waitcnt lgkmcnt(0)
	s_barrier
	s_setprio 1
	s_waitcnt lgkmcnt(0)
	v_mfma_f32_16x16x32_bf16 v[62:65], v[136:139], v[168:171], v[62:65]
	v_mfma_f32_16x16x32_bf16 v[58:61], v[144:147], v[168:171], v[58:61]
	v_mfma_f32_16x16x32_bf16 v[54:57], v[136:139], v[176:179], v[54:57]
	v_mfma_f32_16x16x32_bf16 v[50:53], v[144:147], v[176:179], v[50:53]
	v_mfma_f32_16x16x32_bf16 v[38:41], v[136:139], v[190:193], v[38:41]
	v_mfma_f32_16x16x32_bf16 v[34:37], v[144:147], v[190:193], v[34:37]
	v_mfma_f32_16x16x32_bf16 v[22:25], v[136:139], v[214:217], v[22:25]
	v_mfma_f32_16x16x32_bf16 v[18:21], v[144:147], v[214:217], v[18:21]
	v_mfma_f32_16x16x32_bf16 v[62:65], v[140:143], v[172:175], v[62:65]
	v_mfma_f32_16x16x32_bf16 v[58:61], v[148:151], v[172:175], v[58:61]
	v_mfma_f32_16x16x32_bf16 v[54:57], v[140:143], v[186:189], v[54:57]
	v_mfma_f32_16x16x32_bf16 v[50:53], v[148:151], v[186:189], v[50:53]
	v_mfma_f32_16x16x32_bf16 v[38:41], v[140:143], v[194:197], v[38:41]
	v_mfma_f32_16x16x32_bf16 v[34:37], v[148:151], v[194:197], v[34:37]
	v_mfma_f32_16x16x32_bf16 v[22:25], v[140:143], v[218:221], v[22:25]
	v_mfma_f32_16x16x32_bf16 v[18:21], v[148:151], v[218:221], v[18:21]
	v_mfma_f32_16x16x32_bf16 v[46:49], v[152:155], v[168:171], v[46:49]
	v_mfma_f32_16x16x32_bf16 v[42:45], v[160:163], v[168:171], v[42:45]
	v_mfma_f32_16x16x32_bf16 v[30:33], v[152:155], v[176:179], v[30:33]
	v_mfma_f32_16x16x32_bf16 v[26:29], v[160:163], v[176:179], v[26:29]
	v_mfma_f32_16x16x32_bf16 v[14:17], v[152:155], v[190:193], v[14:17]
	v_mfma_f32_16x16x32_bf16 v[10:13], v[160:163], v[190:193], v[10:13]
	v_mfma_f32_16x16x32_bf16 v[6:9], v[152:155], v[214:217], v[6:9]
	v_mfma_f32_16x16x32_bf16 v[2:5], v[160:163], v[214:217], v[2:5]
	v_mfma_f32_16x16x32_bf16 v[46:49], v[156:159], v[172:175], v[46:49]
	v_mfma_f32_16x16x32_bf16 v[42:45], v[164:167], v[172:175], v[42:45]
	v_mfma_f32_16x16x32_bf16 v[30:33], v[156:159], v[186:189], v[30:33]
	v_mfma_f32_16x16x32_bf16 v[26:29], v[164:167], v[186:189], v[26:29]
	v_mfma_f32_16x16x32_bf16 v[14:17], v[156:159], v[194:197], v[14:17]
	v_mfma_f32_16x16x32_bf16 v[10:13], v[164:167], v[194:197], v[10:13]
	v_mfma_f32_16x16x32_bf16 v[6:9], v[156:159], v[218:221], v[6:9]
	v_mfma_f32_16x16x32_bf16 v[2:5], v[164:167], v[218:221], v[2:5]
	s_setprio 0
	s_barrier
	ds_read_b128 v[136:139], v224
	ds_read_b128 v[140:143], v224 offset:1024
	ds_read_b128 v[144:147], v224 offset:2048
	ds_read_b128 v[148:151], v224 offset:3072
	ds_read_b128 v[152:155], v225
	ds_read_b128 v[156:159], v225 offset:1024
	ds_read_b128 v[160:163], v225 offset:2048
	ds_read_b128 v[164:167], v225 offset:3072
	s_add_u32 s50, s10, 0xb0180
	s_addc_u32 s51, s11, 0
	s_mov_b32 m0, s47
	v_lshl_add_u64 v[180:181], s[50:51], 0, v[0:1]
	ds_read_b128 v[168:171], v135
	ds_read_b128 v[172:175], v135 offset:1024
	ds_read_b128 v[176:179], v135 offset:2048
	ds_read_b128 v[186:189], v135 offset:3072
	ds_read_b128 v[190:193], v135 offset:4096
	ds_read_b128 v[194:197], v135 offset:5120
	ds_read_b128 v[214:217], v135 offset:6144
	ds_read_b128 v[218:221], v135 offset:7168
	global_load_lds_dwordx4 v[180:181], off
	v_lshl_add_u64 v[180:181], s[50:51], 0, v[130:131]
	s_mov_b32 m0, s0
	s_nop 0
	global_load_lds_dwordx4 v[180:181], off
	s_waitcnt vmcnt(8)
	s_waitcnt lgkmcnt(0)
	s_barrier
	s_setprio 1
	s_waitcnt lgkmcnt(0)
	v_mfma_f32_16x16x32_bf16 v[126:129], v[136:139], v[168:171], v[126:129]
	v_mfma_f32_16x16x32_bf16 v[122:125], v[144:147], v[168:171], v[122:125]
	v_mfma_f32_16x16x32_bf16 v[118:121], v[136:139], v[176:179], v[118:121]
	v_mfma_f32_16x16x32_bf16 v[114:117], v[144:147], v[176:179], v[114:117]
	v_mfma_f32_16x16x32_bf16 v[110:113], v[136:139], v[190:193], v[110:113]
	v_mfma_f32_16x16x32_bf16 v[106:109], v[144:147], v[190:193], v[106:109]
	v_mfma_f32_16x16x32_bf16 v[86:89], v[136:139], v[214:217], v[86:89]
	v_mfma_f32_16x16x32_bf16 v[78:81], v[144:147], v[214:217], v[78:81]
	v_mfma_f32_16x16x32_bf16 v[126:129], v[140:143], v[172:175], v[126:129]
	v_mfma_f32_16x16x32_bf16 v[122:125], v[148:151], v[172:175], v[122:125]
	v_mfma_f32_16x16x32_bf16 v[118:121], v[140:143], v[186:189], v[118:121]
	v_mfma_f32_16x16x32_bf16 v[114:117], v[148:151], v[186:189], v[114:117]
	v_mfma_f32_16x16x32_bf16 v[110:113], v[140:143], v[194:197], v[110:113]
	v_mfma_f32_16x16x32_bf16 v[106:109], v[148:151], v[194:197], v[106:109]
	v_mfma_f32_16x16x32_bf16 v[86:89], v[140:143], v[218:221], v[86:89]
	v_mfma_f32_16x16x32_bf16 v[78:81], v[148:151], v[218:221], v[78:81]
	v_mfma_f32_16x16x32_bf16 v[102:105], v[152:155], v[168:171], v[102:105]
	v_mfma_f32_16x16x32_bf16 v[98:101], v[160:163], v[168:171], v[98:101]
	v_mfma_f32_16x16x32_bf16 v[94:97], v[152:155], v[176:179], v[94:97]
	v_mfma_f32_16x16x32_bf16 v[90:93], v[160:163], v[176:179], v[90:93]
	v_mfma_f32_16x16x32_bf16 v[82:85], v[152:155], v[190:193], v[82:85]
	v_mfma_f32_16x16x32_bf16 v[74:77], v[160:163], v[190:193], v[74:77]
	v_mfma_f32_16x16x32_bf16 v[70:73], v[152:155], v[214:217], v[70:73]
	v_mfma_f32_16x16x32_bf16 v[66:69], v[160:163], v[214:217], v[66:69]
	v_mfma_f32_16x16x32_bf16 v[102:105], v[156:159], v[172:175], v[102:105]
	v_mfma_f32_16x16x32_bf16 v[98:101], v[164:167], v[172:175], v[98:101]
	v_mfma_f32_16x16x32_bf16 v[94:97], v[156:159], v[186:189], v[94:97]
	v_mfma_f32_16x16x32_bf16 v[90:93], v[164:167], v[186:189], v[90:93]
	v_mfma_f32_16x16x32_bf16 v[82:85], v[156:159], v[194:197], v[82:85]
	v_mfma_f32_16x16x32_bf16 v[74:77], v[164:167], v[194:197], v[74:77]
	v_mfma_f32_16x16x32_bf16 v[70:73], v[156:159], v[218:221], v[70:73]
	v_mfma_f32_16x16x32_bf16 v[66:69], v[164:167], v[218:221], v[66:69]
	s_setprio 0
	s_barrier
	s_mov_b32 m0, s44
	v_lshl_add_u64 v[180:181], s[24:25], 0, v[0:1]
	s_add_u32 s0, s24, 0xb0000
	ds_read_b128 v[168:171], v135 offset:16384
	ds_read_b128 v[172:175], v135 offset:17408
	ds_read_b128 v[176:179], v135 offset:18432
	ds_read_b128 v[186:189], v135 offset:19456
	ds_read_b128 v[190:193], v135 offset:20480
	ds_read_b128 v[194:197], v135 offset:21504
	ds_read_b128 v[214:217], v135 offset:22528
	ds_read_b128 v[218:221], v135 offset:23552
	global_load_lds_dwordx4 v[180:181], off
	v_lshl_add_u64 v[182:183], s[24:25], 0, v[130:131]
	s_mov_b32 m0, s1
	s_addc_u32 s1, s25, 0
	global_load_lds_dwordx4 v[182:183], off
	v_lshl_add_u64 v[184:185], s[0:1], 0, v[0:1]
	s_mov_b32 m0, s9
	v_lshl_add_u64 v[210:211], s[22:23], 0, v[130:131]
	global_load_lds_dwordx4 v[184:185], off
	v_lshl_add_u64 v[184:185], s[0:1], 0, v[130:131]
	s_mov_b32 m0, s43
	s_nop 0
	global_load_lds_dwordx4 v[184:185], off
	v_lshl_add_u64 v[184:185], s[22:23], 0, v[0:1]
	s_mov_b32 m0, s13
	s_nop 0
	global_load_lds_dwordx4 v[184:185], off
	s_mov_b32 m0, s28
	s_nop 0
	global_load_lds_dwordx4 v[210:211], off
	s_waitcnt vmcnt(8)
	s_waitcnt lgkmcnt(0)
	s_barrier
	s_setprio 1
	s_waitcnt lgkmcnt(0)
	v_mfma_f32_16x16x32_bf16 v[62:65], v[136:139], v[168:171], v[62:65]
	v_mfma_f32_16x16x32_bf16 v[58:61], v[144:147], v[168:171], v[58:61]
	v_mfma_f32_16x16x32_bf16 v[54:57], v[136:139], v[176:179], v[54:57]
	v_mfma_f32_16x16x32_bf16 v[50:53], v[144:147], v[176:179], v[50:53]
	v_mfma_f32_16x16x32_bf16 v[38:41], v[136:139], v[190:193], v[38:41]
	v_mfma_f32_16x16x32_bf16 v[34:37], v[144:147], v[190:193], v[34:37]
	v_mfma_f32_16x16x32_bf16 v[22:25], v[136:139], v[214:217], v[22:25]
	v_mfma_f32_16x16x32_bf16 v[18:21], v[144:147], v[214:217], v[18:21]
	v_mfma_f32_16x16x32_bf16 v[62:65], v[140:143], v[172:175], v[62:65]
	v_mfma_f32_16x16x32_bf16 v[58:61], v[148:151], v[172:175], v[58:61]
	v_mfma_f32_16x16x32_bf16 v[54:57], v[140:143], v[186:189], v[54:57]
	v_mfma_f32_16x16x32_bf16 v[50:53], v[148:151], v[186:189], v[50:53]
	v_mfma_f32_16x16x32_bf16 v[38:41], v[140:143], v[194:197], v[38:41]
	v_mfma_f32_16x16x32_bf16 v[34:37], v[148:151], v[194:197], v[34:37]
	v_mfma_f32_16x16x32_bf16 v[22:25], v[140:143], v[218:221], v[22:25]
	v_mfma_f32_16x16x32_bf16 v[18:21], v[148:151], v[218:221], v[18:21]
	v_mfma_f32_16x16x32_bf16 v[46:49], v[152:155], v[168:171], v[46:49]
	v_mfma_f32_16x16x32_bf16 v[42:45], v[160:163], v[168:171], v[42:45]
	v_mfma_f32_16x16x32_bf16 v[30:33], v[152:155], v[176:179], v[30:33]
	v_mfma_f32_16x16x32_bf16 v[26:29], v[160:163], v[176:179], v[26:29]
	v_mfma_f32_16x16x32_bf16 v[14:17], v[152:155], v[190:193], v[14:17]
	v_mfma_f32_16x16x32_bf16 v[10:13], v[160:163], v[190:193], v[10:13]
	v_mfma_f32_16x16x32_bf16 v[6:9], v[152:155], v[214:217], v[6:9]
	v_mfma_f32_16x16x32_bf16 v[2:5], v[160:163], v[214:217], v[2:5]
	v_mfma_f32_16x16x32_bf16 v[46:49], v[156:159], v[172:175], v[46:49]
	v_mfma_f32_16x16x32_bf16 v[42:45], v[164:167], v[172:175], v[42:45]
	v_mfma_f32_16x16x32_bf16 v[30:33], v[156:159], v[186:189], v[30:33]
	v_mfma_f32_16x16x32_bf16 v[26:29], v[164:167], v[186:189], v[26:29]
	v_mfma_f32_16x16x32_bf16 v[14:17], v[156:159], v[194:197], v[14:17]
	v_mfma_f32_16x16x32_bf16 v[10:13], v[164:167], v[194:197], v[10:13]
	v_mfma_f32_16x16x32_bf16 v[6:9], v[156:159], v[218:221], v[6:9]
	v_mfma_f32_16x16x32_bf16 v[2:5], v[164:167], v[218:221], v[2:5]
	s_setprio 0
	s_barrier
	ds_read_b128 v[136:139], v226
	ds_read_b128 v[140:143], v226 offset:1024
	ds_read_b128 v[144:147], v226 offset:2048
	ds_read_b128 v[148:151], v226 offset:3072
	ds_read_b128 v[152:155], v227
	ds_read_b128 v[156:159], v227 offset:1024
	ds_read_b128 v[160:163], v227 offset:2048
	ds_read_b128 v[164:167], v227 offset:3072
	s_add_u32 s0, s22, 0xb0000
	s_addc_u32 s1, s23, 0
	s_mov_b32 m0, s29
	v_lshl_add_u64 v[222:223], s[0:1], 0, v[0:1]
	ds_read_b128 v[168:171], v135 offset:32768
	ds_read_b128 v[172:175], v135 offset:33792
	ds_read_b128 v[176:179], v135 offset:34816
	ds_read_b128 v[186:189], v135 offset:35840
	ds_read_b128 v[190:193], v135 offset:36864
	ds_read_b128 v[194:197], v135 offset:37888
	ds_read_b128 v[214:217], v135 offset:38912
	ds_read_b128 v[218:221], v135 offset:39936
	global_load_lds_dwordx4 v[222:223], off
	v_lshl_add_u64 v[222:223], s[0:1], 0, v[130:131]
	s_mov_b32 m0, s30
	s_nop 0
	global_load_lds_dwordx4 v[222:223], off
	s_waitcnt vmcnt(8)
	s_waitcnt lgkmcnt(0)
	s_barrier
	s_setprio 1
	s_waitcnt lgkmcnt(0)
	v_mfma_f32_16x16x32_bf16 v[126:129], v[136:139], v[168:171], v[126:129]
	v_mfma_f32_16x16x32_bf16 v[122:125], v[144:147], v[168:171], v[122:125]
	v_mfma_f32_16x16x32_bf16 v[118:121], v[136:139], v[176:179], v[118:121]
	v_mfma_f32_16x16x32_bf16 v[114:117], v[144:147], v[176:179], v[114:117]
	v_mfma_f32_16x16x32_bf16 v[110:113], v[136:139], v[190:193], v[110:113]
	v_mfma_f32_16x16x32_bf16 v[106:109], v[144:147], v[190:193], v[106:109]
	v_mfma_f32_16x16x32_bf16 v[86:89], v[136:139], v[214:217], v[86:89]
	v_mfma_f32_16x16x32_bf16 v[78:81], v[144:147], v[214:217], v[78:81]
	v_mfma_f32_16x16x32_bf16 v[126:129], v[140:143], v[172:175], v[126:129]
	v_mfma_f32_16x16x32_bf16 v[122:125], v[148:151], v[172:175], v[122:125]
	v_mfma_f32_16x16x32_bf16 v[118:121], v[140:143], v[186:189], v[118:121]
	v_mfma_f32_16x16x32_bf16 v[114:117], v[148:151], v[186:189], v[114:117]
	v_mfma_f32_16x16x32_bf16 v[110:113], v[140:143], v[194:197], v[110:113]
	v_mfma_f32_16x16x32_bf16 v[106:109], v[148:151], v[194:197], v[106:109]
	v_mfma_f32_16x16x32_bf16 v[86:89], v[140:143], v[218:221], v[86:89]
	v_mfma_f32_16x16x32_bf16 v[78:81], v[148:151], v[218:221], v[78:81]
	v_mfma_f32_16x16x32_bf16 v[102:105], v[152:155], v[168:171], v[102:105]
	v_mfma_f32_16x16x32_bf16 v[98:101], v[160:163], v[168:171], v[98:101]
	v_mfma_f32_16x16x32_bf16 v[94:97], v[152:155], v[176:179], v[94:97]
	v_mfma_f32_16x16x32_bf16 v[90:93], v[160:163], v[176:179], v[90:93]
	v_mfma_f32_16x16x32_bf16 v[82:85], v[152:155], v[190:193], v[82:85]
	v_mfma_f32_16x16x32_bf16 v[74:77], v[160:163], v[190:193], v[74:77]
	v_mfma_f32_16x16x32_bf16 v[70:73], v[152:155], v[214:217], v[70:73]
	v_mfma_f32_16x16x32_bf16 v[66:69], v[160:163], v[214:217], v[66:69]
	v_mfma_f32_16x16x32_bf16 v[102:105], v[156:159], v[172:175], v[102:105]
	v_mfma_f32_16x16x32_bf16 v[98:101], v[164:167], v[172:175], v[98:101]
	v_mfma_f32_16x16x32_bf16 v[94:97], v[156:159], v[186:189], v[94:97]
	v_mfma_f32_16x16x32_bf16 v[90:93], v[164:167], v[186:189], v[90:93]
	v_mfma_f32_16x16x32_bf16 v[82:85], v[156:159], v[194:197], v[82:85]
	v_mfma_f32_16x16x32_bf16 v[74:77], v[164:167], v[194:197], v[74:77]
	v_mfma_f32_16x16x32_bf16 v[70:73], v[156:159], v[218:221], v[70:73]
	v_mfma_f32_16x16x32_bf16 v[66:69], v[164:167], v[218:221], v[66:69]
	s_setprio 0
	s_barrier
	s_mov_b32 m0, s49
	v_lshl_add_u64 v[180:181], v[180:181], 0, s[54:55]
	s_add_u32 s0, s24, 0xb0080
	ds_read_b128 v[168:171], v135 offset:49152
	ds_read_b128 v[172:175], v135 offset:50176
	ds_read_b128 v[176:179], v135 offset:51200
	ds_read_b128 v[186:189], v135 offset:52224
	ds_read_b128 v[190:193], v135 offset:53248
	ds_read_b128 v[194:197], v135 offset:54272
	ds_read_b128 v[214:217], v135 offset:55296
	ds_read_b128 v[218:221], v135 offset:56320
	global_load_lds_dwordx4 v[180:181], off
	v_lshl_add_u64 v[180:181], v[182:183], 0, s[54:55]
	s_mov_b32 m0, s45
	s_addc_u32 s1, s25, 0
	global_load_lds_dwordx4 v[180:181], off
	v_lshl_add_u64 v[180:181], s[0:1], 0, v[0:1]
	s_mov_b32 m0, s46
	s_nop 0
	global_load_lds_dwordx4 v[180:181], off
	v_lshl_add_u64 v[180:181], s[0:1], 0, v[130:131]
	s_mov_b32 m0, s48
	s_nop 0
	global_load_lds_dwordx4 v[180:181], off
	v_lshl_add_u64 v[180:181], v[184:185], 0, s[54:55]
	s_mov_b32 m0, s34
	s_nop 0
	global_load_lds_dwordx4 v[180:181], off
	v_lshl_add_u64 v[180:181], v[210:211], 0, s[54:55]
	s_mov_b32 m0, s35
	s_nop 0
	global_load_lds_dwordx4 v[180:181], off
	s_waitcnt vmcnt(8)
	s_waitcnt lgkmcnt(0)
	s_barrier
	s_setprio 1
	s_waitcnt lgkmcnt(0)
	v_mfma_f32_16x16x32_bf16 v[62:65], v[136:139], v[168:171], v[62:65]
	v_mfma_f32_16x16x32_bf16 v[58:61], v[144:147], v[168:171], v[58:61]
	v_mfma_f32_16x16x32_bf16 v[54:57], v[136:139], v[176:179], v[54:57]
	v_mfma_f32_16x16x32_bf16 v[50:53], v[144:147], v[176:179], v[50:53]
	v_mfma_f32_16x16x32_bf16 v[38:41], v[136:139], v[190:193], v[38:41]
	v_mfma_f32_16x16x32_bf16 v[34:37], v[144:147], v[190:193], v[34:37]
	v_mfma_f32_16x16x32_bf16 v[22:25], v[136:139], v[214:217], v[22:25]
	v_mfma_f32_16x16x32_bf16 v[18:21], v[144:147], v[214:217], v[18:21]
	v_mfma_f32_16x16x32_bf16 v[62:65], v[140:143], v[172:175], v[62:65]
	v_mfma_f32_16x16x32_bf16 v[58:61], v[148:151], v[172:175], v[58:61]
	v_mfma_f32_16x16x32_bf16 v[54:57], v[140:143], v[186:189], v[54:57]
	v_mfma_f32_16x16x32_bf16 v[50:53], v[148:151], v[186:189], v[50:53]
	v_mfma_f32_16x16x32_bf16 v[38:41], v[140:143], v[194:197], v[38:41]
	v_mfma_f32_16x16x32_bf16 v[34:37], v[148:151], v[194:197], v[34:37]
	v_mfma_f32_16x16x32_bf16 v[22:25], v[140:143], v[218:221], v[22:25]
	v_mfma_f32_16x16x32_bf16 v[18:21], v[148:151], v[218:221], v[18:21]
	v_mfma_f32_16x16x32_bf16 v[46:49], v[152:155], v[168:171], v[46:49]
	v_mfma_f32_16x16x32_bf16 v[42:45], v[160:163], v[168:171], v[42:45]
	v_mfma_f32_16x16x32_bf16 v[30:33], v[152:155], v[176:179], v[30:33]
	v_mfma_f32_16x16x32_bf16 v[26:29], v[160:163], v[176:179], v[26:29]
	v_mfma_f32_16x16x32_bf16 v[14:17], v[152:155], v[190:193], v[14:17]
	v_mfma_f32_16x16x32_bf16 v[10:13], v[160:163], v[190:193], v[10:13]
	v_mfma_f32_16x16x32_bf16 v[6:9], v[152:155], v[214:217], v[6:9]
	v_mfma_f32_16x16x32_bf16 v[2:5], v[160:163], v[214:217], v[2:5]
	v_mfma_f32_16x16x32_bf16 v[46:49], v[156:159], v[172:175], v[46:49]
	v_mfma_f32_16x16x32_bf16 v[42:45], v[164:167], v[172:175], v[42:45]
	v_mfma_f32_16x16x32_bf16 v[30:33], v[156:159], v[186:189], v[30:33]
	v_mfma_f32_16x16x32_bf16 v[26:29], v[164:167], v[186:189], v[26:29]
	v_mfma_f32_16x16x32_bf16 v[14:17], v[156:159], v[194:197], v[14:17]
	v_mfma_f32_16x16x32_bf16 v[10:13], v[164:167], v[194:197], v[10:13]
	v_mfma_f32_16x16x32_bf16 v[6:9], v[156:159], v[218:221], v[6:9]
	v_mfma_f32_16x16x32_bf16 v[2:5], v[164:167], v[218:221], v[2:5]
	s_setprio 0
	s_barrier
	s_and_b64 vcc, exec, s[38:39]
	s_cbranch_vccnz .LBB0_1259
	s_nop 3
	v_mov_b32_e32 v2, 0
	s_mov_b32 s4, s8
	s_mov_b32 s36, s41
	s_mov_b32 s6, s40
	s_mov_b64 s[2:3], s[24:25]
	s_mov_b64 s[10:11], s[22:23]
	s_mov_b32 s37, s42
	v_mov_b32_e32 v3, v2
	v_mov_b32_e32 v4, v2
	v_mov_b32_e32 v5, v2
	v_mov_b32_e32 v6, v2
	v_mov_b32_e32 v7, v2
	v_mov_b32_e32 v8, v2
	v_mov_b32_e32 v9, v2
	v_mov_b32_e32 v10, v2
	v_mov_b32_e32 v11, v2
	v_mov_b32_e32 v12, v2
	v_mov_b32_e32 v13, v2
	v_mov_b32_e32 v14, v2
	v_mov_b32_e32 v15, v2
	v_mov_b32_e32 v16, v2
	v_mov_b32_e32 v17, v2
	v_mov_b32_e32 v26, v2
	v_mov_b32_e32 v27, v2
	v_mov_b32_e32 v28, v2
	v_mov_b32_e32 v29, v2
	v_mov_b32_e32 v30, v2
	v_mov_b32_e32 v31, v2
	v_mov_b32_e32 v32, v2
	v_mov_b32_e32 v33, v2
	v_mov_b32_e32 v42, v2
	v_mov_b32_e32 v43, v2
	v_mov_b32_e32 v44, v2
	v_mov_b32_e32 v45, v2
	v_mov_b32_e32 v46, v2
	v_mov_b32_e32 v47, v2
	v_mov_b32_e32 v48, v2
	v_mov_b32_e32 v49, v2
	v_mov_b32_e32 v18, v2
	v_mov_b32_e32 v19, v2
	v_mov_b32_e32 v20, v2
	v_mov_b32_e32 v21, v2
	v_mov_b32_e32 v22, v2
	v_mov_b32_e32 v23, v2
	v_mov_b32_e32 v24, v2
	v_mov_b32_e32 v25, v2
	v_mov_b32_e32 v34, v2
	v_mov_b32_e32 v35, v2
	v_mov_b32_e32 v36, v2
	v_mov_b32_e32 v37, v2
	v_mov_b32_e32 v38, v2
	v_mov_b32_e32 v39, v2
	v_mov_b32_e32 v40, v2
	v_mov_b32_e32 v41, v2
	v_mov_b32_e32 v50, v2
	v_mov_b32_e32 v51, v2
	v_mov_b32_e32 v52, v2
	v_mov_b32_e32 v53, v2
	v_mov_b32_e32 v54, v2
	v_mov_b32_e32 v55, v2
	v_mov_b32_e32 v56, v2
	v_mov_b32_e32 v57, v2
	v_mov_b32_e32 v58, v2
	v_mov_b32_e32 v59, v2
	v_mov_b32_e32 v60, v2
	v_mov_b32_e32 v61, v2
	v_mov_b32_e32 v62, v2
	v_mov_b32_e32 v63, v2
	v_mov_b32_e32 v64, v2
	v_mov_b32_e32 v65, v2
	v_mov_b32_e32 v66, v2
	v_mov_b32_e32 v67, v2
	v_mov_b32_e32 v68, v2
	v_mov_b32_e32 v69, v2
	v_mov_b32_e32 v70, v2
	v_mov_b32_e32 v71, v2
	v_mov_b32_e32 v72, v2
	v_mov_b32_e32 v73, v2
	v_mov_b32_e32 v74, v2
	v_mov_b32_e32 v75, v2
	v_mov_b32_e32 v76, v2
	v_mov_b32_e32 v77, v2
	v_mov_b32_e32 v82, v2
	v_mov_b32_e32 v83, v2
	v_mov_b32_e32 v84, v2
	v_mov_b32_e32 v85, v2
	v_mov_b32_e32 v90, v2
	v_mov_b32_e32 v91, v2
	v_mov_b32_e32 v92, v2
	v_mov_b32_e32 v93, v2
	v_mov_b32_e32 v94, v2
	v_mov_b32_e32 v95, v2
	v_mov_b32_e32 v96, v2
	v_mov_b32_e32 v97, v2
	v_mov_b32_e32 v98, v2
	v_mov_b32_e32 v99, v2
	v_mov_b32_e32 v100, v2
	v_mov_b32_e32 v101, v2
	v_mov_b32_e32 v102, v2
	v_mov_b32_e32 v103, v2
	v_mov_b32_e32 v104, v2
	v_mov_b32_e32 v105, v2
	v_mov_b32_e32 v78, v2
	v_mov_b32_e32 v79, v2
	v_mov_b32_e32 v80, v2
	v_mov_b32_e32 v81, v2
	v_mov_b32_e32 v86, v2
	v_mov_b32_e32 v87, v2
	v_mov_b32_e32 v88, v2
	v_mov_b32_e32 v89, v2
	v_mov_b32_e32 v106, v2
	v_mov_b32_e32 v107, v2
	v_mov_b32_e32 v108, v2
	v_mov_b32_e32 v109, v2
	v_mov_b32_e32 v110, v2
	v_mov_b32_e32 v111, v2
	v_mov_b32_e32 v112, v2
	v_mov_b32_e32 v113, v2
	v_mov_b32_e32 v114, v2
	v_mov_b32_e32 v115, v2
	v_mov_b32_e32 v116, v2
	v_mov_b32_e32 v117, v2
	v_mov_b32_e32 v118, v2
	v_mov_b32_e32 v119, v2
	v_mov_b32_e32 v120, v2
	v_mov_b32_e32 v121, v2
	v_mov_b32_e32 v122, v2
	v_mov_b32_e32 v123, v2
	v_mov_b32_e32 v124, v2
	v_mov_b32_e32 v125, v2
	v_mov_b32_e32 v126, v2
	v_mov_b32_e32 v127, v2
	v_mov_b32_e32 v128, v2
	v_mov_b32_e32 v129, v2
	s_branch .LBB0_1259
